# WY producer: next-task operand prefetch rewritten by hand with scalar row pointers and saddr loads (about 200 instructions instead of 700); 16-bit values packed after the solve instead of being waited
# speedup vs baseline: 1.0212x; 1.0091x over previous
; #define AIN(i) ld_ptr(c.la + 2 * (i))
; __device__ __forceinline__ void wy_prefetch(const Ctx& c, WyPre& P, int l, int tk, int lane, int wid) {
;     const int hh = tk & 7, ch = (tk >> 3) & 63, b = tk >> 9; const size_t row0 = (size_t)b * SEQ + 64 * ch;
;     const bf16* H = (const bf16*)(AWS + WS_H); const float* HS = (const float*)(AWS + WS_HS); const float* cw = (const float*)AIN(I_GCW) + (size_t)l * 4 * GQKV;
; #pragma unroll
;     for (int j = 0; j < 3; ++j) {
; #pragma unroll
;         for (int r = 0; r < 11; ++r) { const int rr = 8 * wid + r - 3;
;             P.hx[j][r] = (ch == 0 && rr < 0) ? (unsigned short)0 : __builtin_nontemporal_load(H + (size_t)((long long)row0 + rr) * HW + HGQKV + j * 512 + hh * 64 + lane); }
; #pragma unroll
;         for (int i = 0; i < 4; ++i) P.cw[j][i] = cw[(size_t)i * GQKV + j * 512 + hh * 64 + lane]; }
;     P.sa = 0.f; P.sb = 0.f;
;     if (wid == 0) { P.sa = HS[(row0 + lane) * 64 + 24 + hh]; P.sb = HS[(row0 + lane) * 64 + 32 + hh]; }
; }
.LBB0_1045:
	ds_read_b32 v20, v1 offset:464
	ds_read_b32 v21, v1 offset:468
	ds_read_b32 v22, v1 offset:360
	ds_read_b32 v23, v1 offset:364
	v_readlane_b32 s13, v254, 46
	v_readlane_b32 s16, v254, 54
	s_and_b32 s2, s12, 7
	s_bfe_u32 s3, s12, 0x60003
	s_lshr_b32 s4, s12, 9
	s_lshl_b32 s4, s4, 12
	s_lshl_b32 s5, s3, 6
	s_add_i32 s4, s4, s5
	s_lshl_b32 s5, s13, 3
	s_add_i32 s5, s4, s5
	s_add_i32 s5, s5, -3
	s_or_b32 s6, s13, s3
	s_cmp_eq_u32 s6, 0
	s_cselect_b32 s17, 3, 0
	s_add_i32 s5, s5, s17
	s_mul_i32 s6, s5, 0x1c00
	s_lshl_b32 s7, s2, 7
	s_add_i32 s6, s6, s7
	s_add_i32 s6, s6, 0xfd00a00
	s_mul_i32 s7, s16, 0xc00
	s_lshl_b32 s19, s2, 8
	s_add_i32 s7, s7, s19
	s_waitcnt lgkmcnt(0)
	v_readfirstlane_b32 s8, v20
	v_readfirstlane_b32 s9, v21
	v_readfirstlane_b32 s10, v22
	v_readfirstlane_b32 s11, v23
	v_lshlrev_b32_e32 v20, 1, v88
	v_lshlrev_b32_e32 v21, 2, v88
	v_add_u32_e32 v22, 0x1000, v21
	s_add_u32 s24, s8, s6
	s_addc_u32 s25, s9, 0
	s_add_u32 s22, s10, s7
	s_addc_u32 s23, s11, 0
	v_mov_b32_e32 v206, 0
	v_mov_b32_e32 v207, 0
	v_mov_b32_e32 v208, 0
	v_mov_b32_e32 v216, 0
	v_mov_b32_e32 v217, 0
	v_mov_b32_e32 v218, 0
	v_mov_b32_e32 v98, 0
	v_mov_b32_e32 v97, 0
	v_mov_b32_e32 v100, 0
	s_mov_b64 s[26:27], s[22:23]
	global_load_dword v85, v21, s[26:27] offset:0
	s_add_u32 s26, s26, 0x1800
	s_addc_u32 s27, s27, 0
	global_load_dword v84, v21, s[26:27] offset:0
	s_add_u32 s26, s26, 0x1800
	s_addc_u32 s27, s27, 0
	global_load_dword v87, v21, s[26:27] offset:0
	s_add_u32 s26, s26, 0x1800
	s_addc_u32 s27, s27, 0
	global_load_dword v86, v21, s[26:27] offset:0
	s_mov_b64 s[26:27], s[24:25]
	s_cmp_lg_u32 s17, 0
	s_cbranch_scc1 .Lwp_r3_0
	global_load_ushort v206, v20, s[26:27] nt
	s_add_u32 s26, s26, 0x1c00
	s_addc_u32 s27, s27, 0
	global_load_ushort v207, v20, s[26:27] nt
	s_add_u32 s26, s26, 0x1c00
	s_addc_u32 s27, s27, 0
	global_load_ushort v208, v20, s[26:27] nt
	s_add_u32 s26, s26, 0x1c00
	s_addc_u32 s27, s27, 0
.Lwp_r3_0:
	global_load_ushort v209, v20, s[26:27] nt
	s_add_u32 s26, s26, 0x1c00
	s_addc_u32 s27, s27, 0
	global_load_ushort v210, v20, s[26:27] nt
	s_add_u32 s26, s26, 0x1c00
	s_addc_u32 s27, s27, 0
	global_load_ushort v211, v20, s[26:27] nt
	s_add_u32 s26, s26, 0x1c00
	s_addc_u32 s27, s27, 0
	global_load_ushort v212, v20, s[26:27] nt
	s_add_u32 s26, s26, 0x1c00
	s_addc_u32 s27, s27, 0
	global_load_ushort v213, v20, s[26:27] nt
	s_add_u32 s26, s26, 0x1c00
	s_addc_u32 s27, s27, 0
	global_load_ushort v214, v20, s[26:27] nt
	s_add_u32 s26, s26, 0x1c00
	s_addc_u32 s27, s27, 0
	global_load_ushort v215, v20, s[26:27] nt
	s_add_u32 s26, s26, 0x1c00
	s_addc_u32 s27, s27, 0
	global_load_ushort v94, v20, s[26:27] nt
	s_mov_b64 s[26:27], s[22:23]
	global_load_dword v91, v21, s[26:27] offset:2048
	s_add_u32 s26, s26, 0x1800
	s_addc_u32 s27, s27, 0
	global_load_dword v90, v21, s[26:27] offset:2048
	s_add_u32 s26, s26, 0x1800
	s_addc_u32 s27, s27, 0
	global_load_dword v93, v21, s[26:27] offset:2048
	s_add_u32 s26, s26, 0x1800
	s_addc_u32 s27, s27, 0
	global_load_dword v92, v21, s[26:27] offset:2048
	s_mov_b64 s[26:27], s[24:25]
	s_cmp_lg_u32 s17, 0
	s_cbranch_scc1 .Lwp_r3_1
	global_load_ushort v216, v20, s[26:27] offset:1024 nt
	s_add_u32 s26, s26, 0x1c00
	s_addc_u32 s27, s27, 0
	global_load_ushort v217, v20, s[26:27] offset:1024 nt
	s_add_u32 s26, s26, 0x1c00
	s_addc_u32 s27, s27, 0
	global_load_ushort v218, v20, s[26:27] offset:1024 nt
	s_add_u32 s26, s26, 0x1c00
	s_addc_u32 s27, s27, 0
.Lwp_r3_1:
	global_load_ushort v219, v20, s[26:27] offset:1024 nt
	s_add_u32 s26, s26, 0x1c00
	s_addc_u32 s27, s27, 0
	global_load_ushort v230, v20, s[26:27] offset:1024 nt
	s_add_u32 s26, s26, 0x1c00
	s_addc_u32 s27, s27, 0
	global_load_ushort v231, v20, s[26:27] offset:1024 nt
	s_add_u32 s26, s26, 0x1c00
	s_addc_u32 s27, s27, 0
	global_load_ushort v232, v20, s[26:27] offset:1024 nt
	s_add_u32 s26, s26, 0x1c00
	s_addc_u32 s27, s27, 0
	global_load_ushort v233, v20, s[26:27] offset:1024 nt
	s_add_u32 s26, s26, 0x1c00
	s_addc_u32 s27, s27, 0
	global_load_ushort v234, v20, s[26:27] offset:1024 nt
	s_add_u32 s26, s26, 0x1c00
	s_addc_u32 s27, s27, 0
	global_load_ushort v235, v20, s[26:27] offset:1024 nt
	s_add_u32 s26, s26, 0x1c00
	s_addc_u32 s27, s27, 0
	global_load_ushort v96, v20, s[26:27] offset:1024 nt
	s_mov_b64 s[26:27], s[22:23]
	global_load_dword v108, v22, s[26:27]
	s_add_u32 s26, s26, 0x1800
	s_addc_u32 s27, s27, 0
	global_load_dword v110, v22, s[26:27]
	s_add_u32 s26, s26, 0x1800
	s_addc_u32 s27, s27, 0
	global_load_dword v112, v22, s[26:27]
	s_add_u32 s26, s26, 0x1800
	s_addc_u32 s27, s27, 0
	global_load_dword v113, v22, s[26:27]
	s_mov_b64 s[26:27], s[24:25]
	s_cmp_lg_u32 s17, 0
	s_cbranch_scc1 .Lwp_r3_2
	global_load_ushort v98, v20, s[26:27] offset:2048 nt
	s_add_u32 s26, s26, 0x1c00
	s_addc_u32 s27, s27, 0
	global_load_ushort v97, v20, s[26:27] offset:2048 nt
	s_add_u32 s26, s26, 0x1c00
	s_addc_u32 s27, s27, 0
	global_load_ushort v100, v20, s[26:27] offset:2048 nt
	s_add_u32 s26, s26, 0x1c00
	s_addc_u32 s27, s27, 0
.Lwp_r3_2:
	global_load_ushort v99, v20, s[26:27] offset:2048 nt
	s_add_u32 s26, s26, 0x1c00
	s_addc_u32 s27, s27, 0
	global_load_ushort v101, v20, s[26:27] offset:2048 nt
	s_add_u32 s26, s26, 0x1c00
	s_addc_u32 s27, s27, 0
	global_load_ushort v102, v20, s[26:27] offset:2048 nt
	s_add_u32 s26, s26, 0x1c00
	s_addc_u32 s27, s27, 0
	global_load_ushort v104, v20, s[26:27] offset:2048 nt
	s_add_u32 s26, s26, 0x1c00
	s_addc_u32 s27, s27, 0
	global_load_ushort v103, v20, s[26:27] offset:2048 nt
	s_add_u32 s26, s26, 0x1c00
	s_addc_u32 s27, s27, 0
	global_load_ushort v105, v20, s[26:27] offset:2048 nt
	s_add_u32 s26, s26, 0x1c00
	s_addc_u32 s27, s27, 0
	global_load_ushort v106, v20, s[26:27] offset:2048 nt
	s_add_u32 s26, s26, 0x1c00
	s_addc_u32 s27, s27, 0
	global_load_ushort v107, v20, s[26:27] offset:2048 nt
	s_cmp_lg_u32 s13, 0
	s_cbranch_scc1 .LBB0_1086
	s_lshl_b32 s6, s4, 8
	s_lshl_b32 s7, s2, 2
	s_add_i32 s6, s6, s7
	s_add_i32 s6, s6, 0x16f00000
	s_add_u32 s26, s8, s6
	s_addc_u32 s27, s9, 0
	v_lshlrev_b32_e32 v23, 8, v88
	global_load_dword v111, v23, s[26:27] offset:96
	global_load_dword v109, v23, s[26:27] offset:128
; #define LAS __attribute__((address_space(3)))
; #define WY_RDBLK(m_) do { _Pragma("unroll") for (int t_ = 0; t_ <= (m_); ++t_) LB[(m_) & 1][t_] = *(const LAS f32x4*)(lq + (m_) * WY_BS + 4 * t_); } while (0)
; __device__ __forceinline__ int wy_producer_task(const Ctx& c, int l, int tk, WyPre& P, unsigned* head) {
;     ...
;     {
;         f32x4 LB[2][16];
;         const LAS float* lq = LM + q4 * WY_QS;
;     ...
;         WY_RDBLK(0);
; #pragma unroll
;         for (int m = 0; m < 16; ++m) {
;             if (m + 1 < 16) WY_RDBLK(m + 1);
;             __builtin_amdgcn_sched_barrier(0);
;             f32x4 pre = (f32x4){0.f, 0.f, 0.f, 0.f};
; #pragma unroll
;             for (int t = 0; t < m; ++t) pre = LB[m & 1][t] * own[t] + pre;
; #pragma unroll
;             for (int rr = 0; rr < 4; ++rr) {
;                 float acc = ((q4 == rr) ? own[m] : 0.f) - pre[rr];
;                 if (rr > 0) acc = fmaf(-LB[m & 1][m][rr], own[m], acc);
;                 const float x = quad_sum(acc);
;                 own[m] = (q4 == rr) ? x : own[m]; }
;             __builtin_amdgcn_sched_barrier(0);
;         }
;     ...
;     }
.LBB0_1086:
.LBB0_1087:
	s_movk_i32 s2, 0x110
	v_mad_u32_u24 v21, v0, s2, 0
	s_waitcnt lgkmcnt(0)
	s_barrier
	ds_read_b128 v[22:25], v21 offset:34304
	ds_read_b128 v[26:29], v21 offset:35392
	ds_read_b128 v[30:33], v21 offset:35408
	v_cmp_eq_u32_e64 s[6:7], 0, v0
	v_cmp_eq_u32_e32 vcc, 1, v0
	v_cmp_eq_u32_e64 s[2:3], 2, v0
	v_cndmask_b32_e64 v20, 0, v18, s[6:7]
	s_waitcnt lgkmcnt(2)
	v_cndmask_b32_e32 v22, 0, v18, vcc
	v_cmp_eq_u32_e64 s[4:5], 3, v0
	v_add_f32_dpp v20, v20, v20 quad_perm:[1,0,3,2] row_mask:0xf bank_mask:0xf bound_ctrl:1
	s_nop 1
	v_add_f32_dpp v20, v20, v20 quad_perm:[2,3,0,1] row_mask:0xf bank_mask:0xf bound_ctrl:1
	v_cndmask_b32_e64 v20, v18, v20, s[6:7]
	v_fma_f32 v22, -v23, v20, v22
	s_nop 1
	v_add_f32_dpp v22, v22, v22 quad_perm:[1,0,3,2] row_mask:0xf bank_mask:0xf bound_ctrl:1
	s_nop 1
	v_add_f32_dpp v22, v22, v22 quad_perm:[2,3,0,1] row_mask:0xf bank_mask:0xf bound_ctrl:1
	v_cndmask_b32_e32 v20, v20, v22, vcc
	v_cndmask_b32_e64 v22, 0, v18, s[2:3]
	v_fma_f32 v22, -v24, v20, v22
	v_cndmask_b32_e64 v18, 0, v18, s[4:5]
	s_nop 0
	v_add_f32_dpp v22, v22, v22 quad_perm:[1,0,3,2] row_mask:0xf bank_mask:0xf bound_ctrl:1
	s_nop 1
	v_add_f32_dpp v22, v22, v22 quad_perm:[2,3,0,1] row_mask:0xf bank_mask:0xf bound_ctrl:1
	v_cndmask_b32_e64 v20, v20, v22, s[2:3]
	v_fma_f32 v18, -v25, v20, v18
	s_nop 1
	v_add_f32_dpp v18, v18, v18 quad_perm:[1,0,3,2] row_mask:0xf bank_mask:0xf bound_ctrl:1
	s_nop 1
	v_add_f32_dpp v18, v18, v18 quad_perm:[2,3,0,1] row_mask:0xf bank_mask:0xf bound_ctrl:1
	v_cndmask_b32_e64 v18, v20, v18, s[4:5]
	ds_read_b128 v[22:25], v21 offset:36480
	ds_read_b128 v[34:37], v21 offset:36496
	ds_read_b128 v[38:41], v21 offset:36512
	s_waitcnt lgkmcnt(4)
	v_pk_fma_f32 v[26:27], v[26:27], v[18:19], 0 op_sel_hi:[1,0,0]
	v_cndmask_b32_e64 v20, 0, v19, s[6:7]
	v_sub_f32_e32 v20, v20, v26
	v_cndmask_b32_e32 v26, 0, v19, vcc
	v_sub_f32_e32 v26, v26, v27
	v_add_f32_dpp v20, v20, v20 quad_perm:[1,0,3,2] row_mask:0xf bank_mask:0xf bound_ctrl:1
	v_pk_fma_f32 v[28:29], v[28:29], v[18:19], 0 op_sel_hi:[1,0,0]
	s_nop 0
	v_add_f32_dpp v20, v20, v20 quad_perm:[2,3,0,1] row_mask:0xf bank_mask:0xf bound_ctrl:1
	v_cndmask_b32_e64 v20, v19, v20, s[6:7]
	s_waitcnt lgkmcnt(3)
	v_fma_f32 v26, -v31, v20, v26
	s_nop 1
	v_add_f32_dpp v26, v26, v26 quad_perm:[1,0,3,2] row_mask:0xf bank_mask:0xf bound_ctrl:1
	s_nop 1
	v_add_f32_dpp v26, v26, v26 quad_perm:[2,3,0,1] row_mask:0xf bank_mask:0xf bound_ctrl:1
	v_cndmask_b32_e32 v20, v20, v26, vcc
	v_cndmask_b32_e64 v26, 0, v19, s[2:3]
	v_sub_f32_e32 v26, v26, v28
	v_fma_f32 v26, -v32, v20, v26
	v_cndmask_b32_e64 v19, 0, v19, s[4:5]
	v_sub_f32_e32 v19, v19, v29
	v_add_f32_dpp v26, v26, v26 quad_perm:[1,0,3,2] row_mask:0xf bank_mask:0xf bound_ctrl:1
	s_nop 1
	v_add_f32_dpp v26, v26, v26 quad_perm:[2,3,0,1] row_mask:0xf bank_mask:0xf bound_ctrl:1
	v_cndmask_b32_e64 v20, v20, v26, s[2:3]
	v_fma_f32 v19, -v33, v20, v19
	s_nop 1
	v_add_f32_dpp v19, v19, v19 quad_perm:[1,0,3,2] row_mask:0xf bank_mask:0xf bound_ctrl:1
	s_nop 1
	v_add_f32_dpp v19, v19, v19 quad_perm:[2,3,0,1] row_mask:0xf bank_mask:0xf bound_ctrl:1
	v_cndmask_b32_e64 v20, v20, v19, s[4:5]
	ds_read_b128 v[26:29], v21 offset:37568
	ds_read_b128 v[30:33], v21 offset:37584
	ds_read_b128 v[42:45], v21 offset:37600
	ds_read_b128 v[46:49], v21 offset:37616
	s_waitcnt lgkmcnt(6)
	v_pk_fma_f32 v[22:23], v[22:23], v[18:19], 0 op_sel_hi:[1,0,0]
	v_pk_fma_f32 v[24:25], v[24:25], v[18:19], 0 op_sel_hi:[1,0,0]
	s_waitcnt lgkmcnt(5)
	v_pk_fma_f32 v[22:23], v[34:35], v[20:21], v[22:23] op_sel_hi:[1,0,1]
	v_cndmask_b32_e64 v19, 0, v16, s[6:7]
	v_sub_f32_e32 v19, v19, v22
	v_cndmask_b32_e32 v22, 0, v16, vcc
	v_sub_f32_e32 v22, v22, v23
	v_add_f32_dpp v19, v19, v19 quad_perm:[1,0,3,2] row_mask:0xf bank_mask:0xf bound_ctrl:1
	v_pk_fma_f32 v[24:25], v[36:37], v[20:21], v[24:25] op_sel_hi:[1,0,1]
	s_nop 0
	v_add_f32_dpp v19, v19, v19 quad_perm:[2,3,0,1] row_mask:0xf bank_mask:0xf bound_ctrl:1
	v_cndmask_b32_e64 v19, v16, v19, s[6:7]
	s_waitcnt lgkmcnt(4)
	v_fma_f32 v22, -v39, v19, v22
	s_nop 1
	v_add_f32_dpp v22, v22, v22 quad_perm:[1,0,3,2] row_mask:0xf bank_mask:0xf bound_ctrl:1
	s_nop 1
	v_add_f32_dpp v22, v22, v22 quad_perm:[2,3,0,1] row_mask:0xf bank_mask:0xf bound_ctrl:1
	v_cndmask_b32_e32 v19, v19, v22, vcc
	v_cndmask_b32_e64 v22, 0, v16, s[2:3]
	v_sub_f32_e32 v22, v22, v24
	v_fma_f32 v22, -v40, v19, v22
	v_cndmask_b32_e64 v16, 0, v16, s[4:5]
	v_sub_f32_e32 v16, v16, v25
	v_add_f32_dpp v22, v22, v22 quad_perm:[1,0,3,2] row_mask:0xf bank_mask:0xf bound_ctrl:1
	s_nop 1
	v_add_f32_dpp v22, v22, v22 quad_perm:[2,3,0,1] row_mask:0xf bank_mask:0xf bound_ctrl:1
	v_cndmask_b32_e64 v19, v19, v22, s[2:3]
	v_fma_f32 v16, -v41, v19, v16
	s_nop 1
	v_add_f32_dpp v16, v16, v16 quad_perm:[1,0,3,2] row_mask:0xf bank_mask:0xf bound_ctrl:1
	s_nop 1
	v_add_f32_dpp v16, v16, v16 quad_perm:[2,3,0,1] row_mask:0xf bank_mask:0xf bound_ctrl:1
	v_cndmask_b32_e64 v16, v19, v16, s[4:5]
	ds_read_b128 v[34:37], v21 offset:38656
	ds_read_b128 v[38:41], v21 offset:38672
	ds_read_b128 v[50:53], v21 offset:38688
	ds_read_b128 v[54:57], v21 offset:38704
	ds_read_b128 v[22:25], v21 offset:38720
	s_waitcnt lgkmcnt(8)
	v_pk_fma_f32 v[26:27], v[18:19], v[26:27], 0 op_sel_hi:[0,1,0]
	s_waitcnt lgkmcnt(7)
	v_pk_fma_f32 v[26:27], v[30:31], v[20:21], v[26:27] op_sel_hi:[1,0,1]
	v_pk_fma_f32 v[28:29], v[18:19], v[28:29], 0 op_sel_hi:[0,1,0]
	s_waitcnt lgkmcnt(6)
	v_pk_fma_f32 v[26:27], v[42:43], v[16:17], v[26:27] op_sel_hi:[1,0,1]
	v_cndmask_b32_e64 v19, 0, v17, s[6:7]
	v_sub_f32_e32 v19, v19, v26
	s_waitcnt lgkmcnt(0)
; #define LAS __attribute__((address_space(3)))
; #define WY_RDBLK(m_) do { _Pragma("unroll") for (int t_ = 0; t_ <= (m_); ++t_) LB[(m_) & 1][t_] = *(const LAS f32x4*)(lq + (m_) * WY_BS + 4 * t_); } while (0)
; __device__ __forceinline__ int wy_producer_task(const Ctx& c, int l, int tk, WyPre& P, unsigned* head) {
;     ...
;     {
;         f32x4 LB[2][16];
;         const LAS float* lq = LM + q4 * WY_QS;
;     ...
;         WY_RDBLK(0);
; #pragma unroll
;         for (int m = 0; m < 16; ++m) {
;             if (m + 1 < 16) WY_RDBLK(m + 1);
;             __builtin_amdgcn_sched_barrier(0);
;             f32x4 pre = (f32x4){0.f, 0.f, 0.f, 0.f};
; #pragma unroll
;             for (int t = 0; t < m; ++t) pre = LB[m & 1][t] * own[t] + pre;
; #pragma unroll
;             for (int rr = 0; rr < 4; ++rr) {
;                 float acc = ((q4 == rr) ? own[m] : 0.f) - pre[rr];
;                 if (rr > 0) acc = fmaf(-LB[m & 1][m][rr], own[m], acc);
;                 const float x = quad_sum(acc);
;                 own[m] = (q4 == rr) ? x : own[m]; }
;             __builtin_amdgcn_sched_barrier(0);
;         }
;     ...
;     }
	v_cndmask_b32_e32 v22, 0, v17, vcc
	v_sub_f32_e32 v22, v22, v27
	v_add_f32_dpp v19, v19, v19 quad_perm:[1,0,3,2] row_mask:0xf bank_mask:0xf bound_ctrl:1
	v_pk_fma_f32 v[28:29], v[32:33], v[20:21], v[28:29] op_sel_hi:[1,0,1]
	s_nop 0
	v_add_f32_dpp v19, v19, v19 quad_perm:[2,3,0,1] row_mask:0xf bank_mask:0xf bound_ctrl:1
	v_cndmask_b32_e64 v19, v17, v19, s[6:7]
	v_fma_f32 v22, -v47, v19, v22
	v_pk_fma_f32 v[28:29], v[44:45], v[16:17], v[28:29] op_sel_hi:[1,0,1]
	s_nop 0
	v_add_f32_dpp v22, v22, v22 quad_perm:[1,0,3,2] row_mask:0xf bank_mask:0xf bound_ctrl:1
	s_nop 1
	v_add_f32_dpp v22, v22, v22 quad_perm:[2,3,0,1] row_mask:0xf bank_mask:0xf bound_ctrl:1
	v_cndmask_b32_e32 v19, v19, v22, vcc
	v_cndmask_b32_e64 v22, 0, v17, s[2:3]
	v_sub_f32_e32 v22, v22, v28
	v_fma_f32 v22, -v48, v19, v22
	v_cndmask_b32_e64 v17, 0, v17, s[4:5]
	v_sub_f32_e32 v17, v17, v29
	v_add_f32_dpp v22, v22, v22 quad_perm:[1,0,3,2] row_mask:0xf bank_mask:0xf bound_ctrl:1
	s_nop 1
	v_add_f32_dpp v22, v22, v22 quad_perm:[2,3,0,1] row_mask:0xf bank_mask:0xf bound_ctrl:1
	v_cndmask_b32_e64 v19, v19, v22, s[2:3]
	v_fma_f32 v17, -v49, v19, v17
	s_nop 1
	v_add_f32_dpp v17, v17, v17 quad_perm:[1,0,3,2] row_mask:0xf bank_mask:0xf bound_ctrl:1
	s_nop 1
	v_add_f32_dpp v17, v17, v17 quad_perm:[2,3,0,1] row_mask:0xf bank_mask:0xf bound_ctrl:1
	v_cndmask_b32_e64 v22, v19, v17, s[4:5]
	ds_read_b128 v[26:29], v21 offset:39744
	ds_read_b128 v[30:33], v21 offset:39760
	ds_read_b128 v[42:45], v21 offset:39776
	ds_read_b128 v[46:49], v21 offset:39792
	ds_read_b128 v[58:61], v21 offset:39808
	ds_read_b128 v[62:65], v21 offset:39824
	v_pk_fma_f32 v[34:35], v[18:19], v[34:35], 0 op_sel_hi:[0,1,0]
	v_pk_fma_f32 v[36:37], v[18:19], v[36:37], 0 op_sel_hi:[0,1,0]
	v_pk_fma_f32 v[34:35], v[38:39], v[20:21], v[34:35] op_sel_hi:[1,0,1]
	v_pk_fma_f32 v[36:37], v[40:41], v[20:21], v[36:37] op_sel_hi:[1,0,1]
	v_pk_fma_f32 v[34:35], v[50:51], v[16:17], v[34:35] op_sel_hi:[1,0,1]
	v_pk_fma_f32 v[36:37], v[52:53], v[16:17], v[36:37] op_sel_hi:[1,0,1]
	v_pk_fma_f32 v[34:35], v[54:55], v[22:23], v[34:35] op_sel_hi:[1,0,1]
	v_cndmask_b32_e64 v17, 0, v14, s[6:7]
	v_sub_f32_e32 v17, v17, v34
	v_cndmask_b32_e32 v19, 0, v14, vcc
	v_sub_f32_e32 v19, v19, v35
	v_add_f32_dpp v17, v17, v17 quad_perm:[1,0,3,2] row_mask:0xf bank_mask:0xf bound_ctrl:1
	v_pk_fma_f32 v[36:37], v[56:57], v[22:23], v[36:37] op_sel_hi:[1,0,1]
	s_nop 0
	v_add_f32_dpp v17, v17, v17 quad_perm:[2,3,0,1] row_mask:0xf bank_mask:0xf bound_ctrl:1
	v_cndmask_b32_e64 v17, v14, v17, s[6:7]
	v_fma_f32 v19, -v23, v17, v19
	s_nop 1
	v_add_f32_dpp v19, v19, v19 quad_perm:[1,0,3,2] row_mask:0xf bank_mask:0xf bound_ctrl:1
	s_nop 1
	v_add_f32_dpp v19, v19, v19 quad_perm:[2,3,0,1] row_mask:0xf bank_mask:0xf bound_ctrl:1
	v_cndmask_b32_e32 v17, v17, v19, vcc
	v_cndmask_b32_e64 v19, 0, v14, s[2:3]
	v_sub_f32_e32 v19, v19, v36
	v_fma_f32 v19, -v24, v17, v19
	v_cndmask_b32_e64 v14, 0, v14, s[4:5]
	v_sub_f32_e32 v14, v14, v37
	v_add_f32_dpp v19, v19, v19 quad_perm:[1,0,3,2] row_mask:0xf bank_mask:0xf bound_ctrl:1
	s_nop 1
	v_add_f32_dpp v19, v19, v19 quad_perm:[2,3,0,1] row_mask:0xf bank_mask:0xf bound_ctrl:1
	v_cndmask_b32_e64 v17, v17, v19, s[2:3]
	v_fma_f32 v14, -v25, v17, v14
	s_nop 1
	v_add_f32_dpp v14, v14, v14 quad_perm:[1,0,3,2] row_mask:0xf bank_mask:0xf bound_ctrl:1
	s_nop 1
	v_add_f32_dpp v14, v14, v14 quad_perm:[2,3,0,1] row_mask:0xf bank_mask:0xf bound_ctrl:1
	v_cndmask_b32_e64 v14, v17, v14, s[4:5]
	ds_read_b128 v[34:37], v21 offset:40832
	ds_read_b128 v[38:41], v21 offset:40848
	ds_read_b128 v[50:53], v21 offset:40864
	ds_read_b128 v[54:57], v21 offset:40880
	ds_read_b128 v[66:69], v21 offset:40896
	ds_read_b128 v[70:73], v21 offset:40912
	ds_read_b128 v[74:77], v21 offset:40928
	s_waitcnt lgkmcnt(12)
	v_pk_fma_f32 v[26:27], v[18:19], v[26:27], 0 op_sel_hi:[0,1,0]
	s_waitcnt lgkmcnt(11)
	v_pk_fma_f32 v[26:27], v[20:21], v[30:31], v[26:27] op_sel_hi:[0,1,1]
	v_pk_fma_f32 v[24:25], v[18:19], v[28:29], 0 op_sel_hi:[0,1,0]
	s_waitcnt lgkmcnt(10)
	v_pk_fma_f32 v[26:27], v[42:43], v[16:17], v[26:27] op_sel_hi:[1,0,1]
	v_pk_fma_f32 v[24:25], v[20:21], v[32:33], v[24:25] op_sel_hi:[0,1,1]
	s_waitcnt lgkmcnt(9)
	v_pk_fma_f32 v[26:27], v[46:47], v[22:23], v[26:27] op_sel_hi:[1,0,1]
	v_pk_fma_f32 v[24:25], v[44:45], v[16:17], v[24:25] op_sel_hi:[1,0,1]
	s_waitcnt lgkmcnt(8)
	v_pk_fma_f32 v[26:27], v[58:59], v[14:15], v[26:27] op_sel_hi:[1,0,1]
	v_cndmask_b32_e64 v17, 0, v15, s[6:7]
	v_sub_f32_e32 v17, v17, v26
	v_cndmask_b32_e32 v19, 0, v15, vcc
	v_sub_f32_e32 v19, v19, v27
	v_add_f32_dpp v17, v17, v17 quad_perm:[1,0,3,2] row_mask:0xf bank_mask:0xf bound_ctrl:1
	v_pk_fma_f32 v[24:25], v[48:49], v[22:23], v[24:25] op_sel_hi:[1,0,1]
	s_nop 0
	v_add_f32_dpp v17, v17, v17 quad_perm:[2,3,0,1] row_mask:0xf bank_mask:0xf bound_ctrl:1
	v_cndmask_b32_e64 v17, v15, v17, s[6:7]
	s_waitcnt lgkmcnt(7)
	v_fma_f32 v19, -v63, v17, v19
	v_pk_fma_f32 v[24:25], v[60:61], v[14:15], v[24:25] op_sel_hi:[1,0,1]
	s_nop 0
	v_add_f32_dpp v19, v19, v19 quad_perm:[1,0,3,2] row_mask:0xf bank_mask:0xf bound_ctrl:1
	s_nop 1
	v_add_f32_dpp v19, v19, v19 quad_perm:[2,3,0,1] row_mask:0xf bank_mask:0xf bound_ctrl:1
	v_cndmask_b32_e32 v17, v17, v19, vcc
	v_cndmask_b32_e64 v19, 0, v15, s[2:3]
	v_sub_f32_e32 v19, v19, v24
	v_fma_f32 v19, -v64, v17, v19
	v_cndmask_b32_e64 v15, 0, v15, s[4:5]
	v_sub_f32_e32 v15, v15, v25
	v_add_f32_dpp v19, v19, v19 quad_perm:[1,0,3,2] row_mask:0xf bank_mask:0xf bound_ctrl:1
	s_nop 1
	v_add_f32_dpp v19, v19, v19 quad_perm:[2,3,0,1] row_mask:0xf bank_mask:0xf bound_ctrl:1
	v_cndmask_b32_e64 v17, v17, v19, s[2:3]
	v_fma_f32 v15, -v65, v17, v15
	s_nop 1
	v_add_f32_dpp v15, v15, v15 quad_perm:[1,0,3,2] row_mask:0xf bank_mask:0xf bound_ctrl:1
	s_nop 1
	v_add_f32_dpp v15, v15, v15 quad_perm:[2,3,0,1] row_mask:0xf bank_mask:0xf bound_ctrl:1
	v_cndmask_b32_e64 v24, v17, v15, s[4:5]
	ds_read_b128 v[26:29], v21 offset:41920
	ds_read_b128 v[30:33], v21 offset:41936
	ds_read_b128 v[42:45], v21 offset:41952
	ds_read_b128 v[46:49], v21 offset:41968
	ds_read_b128 v[58:61], v21 offset:41984
	ds_read_b128 v[62:65], v21 offset:42000
	ds_read_b128 v[78:81], v21 offset:42016
	ds_read_b128 v[126:129], v21 offset:42032
	s_waitcnt lgkmcnt(14)
; #define LAS __attribute__((address_space(3)))
; #define WY_RDBLK(m_) do { _Pragma("unroll") for (int t_ = 0; t_ <= (m_); ++t_) LB[(m_) & 1][t_] = *(const LAS f32x4*)(lq + (m_) * WY_BS + 4 * t_); } while (0)
; __device__ __forceinline__ int wy_producer_task(const Ctx& c, int l, int tk, WyPre& P, unsigned* head) {
;     ...
;     {
;         f32x4 LB[2][16];
;         const LAS float* lq = LM + q4 * WY_QS;
;     ...
;         WY_RDBLK(0);
; #pragma unroll
;         for (int m = 0; m < 16; ++m) {
;             if (m + 1 < 16) WY_RDBLK(m + 1);
;             __builtin_amdgcn_sched_barrier(0);
;             f32x4 pre = (f32x4){0.f, 0.f, 0.f, 0.f};
; #pragma unroll
;             for (int t = 0; t < m; ++t) pre = LB[m & 1][t] * own[t] + pre;
; #pragma unroll
;             for (int rr = 0; rr < 4; ++rr) {
;                 float acc = ((q4 == rr) ? own[m] : 0.f) - pre[rr];
;                 if (rr > 0) acc = fmaf(-LB[m & 1][m][rr], own[m], acc);
;                 const float x = quad_sum(acc);
;                 own[m] = (q4 == rr) ? x : own[m]; }
;             __builtin_amdgcn_sched_barrier(0);
;         }
;     ...
;     }
	v_pk_fma_f32 v[34:35], v[18:19], v[34:35], 0 op_sel_hi:[0,1,0]
	v_pk_fma_f32 v[36:37], v[18:19], v[36:37], 0 op_sel_hi:[0,1,0]
	s_waitcnt lgkmcnt(13)
	v_pk_fma_f32 v[34:35], v[20:21], v[38:39], v[34:35] op_sel_hi:[0,1,1]
	v_pk_fma_f32 v[36:37], v[20:21], v[40:41], v[36:37] op_sel_hi:[0,1,1]
	s_waitcnt lgkmcnt(12)
	v_pk_fma_f32 v[34:35], v[16:17], v[50:51], v[34:35] op_sel_hi:[0,1,1]
	v_pk_fma_f32 v[36:37], v[16:17], v[52:53], v[36:37] op_sel_hi:[0,1,1]
	s_waitcnt lgkmcnt(11)
	v_pk_fma_f32 v[34:35], v[54:55], v[22:23], v[34:35] op_sel_hi:[1,0,1]
	v_pk_fma_f32 v[36:37], v[56:57], v[22:23], v[36:37] op_sel_hi:[1,0,1]
	s_waitcnt lgkmcnt(10)
	v_pk_fma_f32 v[34:35], v[66:67], v[14:15], v[34:35] op_sel_hi:[1,0,1]
	v_pk_fma_f32 v[36:37], v[68:69], v[14:15], v[36:37] op_sel_hi:[1,0,1]
	s_waitcnt lgkmcnt(9)
	v_pk_fma_f32 v[34:35], v[70:71], v[24:25], v[34:35] op_sel_hi:[1,0,1]
	v_cndmask_b32_e64 v15, 0, v12, s[6:7]
	v_sub_f32_e32 v15, v15, v34
	v_cndmask_b32_e32 v17, 0, v12, vcc
	v_sub_f32_e32 v17, v17, v35
	v_add_f32_dpp v15, v15, v15 quad_perm:[1,0,3,2] row_mask:0xf bank_mask:0xf bound_ctrl:1
	v_pk_fma_f32 v[36:37], v[72:73], v[24:25], v[36:37] op_sel_hi:[1,0,1]
	s_nop 0
	v_add_f32_dpp v15, v15, v15 quad_perm:[2,3,0,1] row_mask:0xf bank_mask:0xf bound_ctrl:1
	v_cndmask_b32_e64 v15, v12, v15, s[6:7]
	s_waitcnt lgkmcnt(8)
	v_fma_f32 v17, -v75, v15, v17
	s_nop 1
	v_add_f32_dpp v17, v17, v17 quad_perm:[1,0,3,2] row_mask:0xf bank_mask:0xf bound_ctrl:1
	s_nop 1
	v_add_f32_dpp v17, v17, v17 quad_perm:[2,3,0,1] row_mask:0xf bank_mask:0xf bound_ctrl:1
	v_cndmask_b32_e32 v15, v15, v17, vcc
	v_cndmask_b32_e64 v17, 0, v12, s[2:3]
	v_sub_f32_e32 v17, v17, v36
	v_fma_f32 v17, -v76, v15, v17
	v_cndmask_b32_e64 v12, 0, v12, s[4:5]
	v_sub_f32_e32 v12, v12, v37
	v_add_f32_dpp v17, v17, v17 quad_perm:[1,0,3,2] row_mask:0xf bank_mask:0xf bound_ctrl:1
	s_nop 1
	v_add_f32_dpp v17, v17, v17 quad_perm:[2,3,0,1] row_mask:0xf bank_mask:0xf bound_ctrl:1
	v_cndmask_b32_e64 v15, v15, v17, s[2:3]
	v_fma_f32 v12, -v77, v15, v12
	s_nop 1
	v_add_f32_dpp v12, v12, v12 quad_perm:[1,0,3,2] row_mask:0xf bank_mask:0xf bound_ctrl:1
	s_nop 1
	v_add_f32_dpp v12, v12, v12 quad_perm:[2,3,0,1] row_mask:0xf bank_mask:0xf bound_ctrl:1
	v_cndmask_b32_e64 v12, v15, v12, s[4:5]
	ds_read_b128 v[34:37], v21 offset:43008
	ds_read_b128 v[38:41], v21 offset:43024
	ds_read_b128 v[50:53], v21 offset:43040
	ds_read_b128 v[54:57], v21 offset:43056
	ds_read_b128 v[66:69], v21 offset:43072
	ds_read_b128 v[70:73], v21 offset:43088
	ds_read_b128 v[74:77], v21 offset:43104
	ds_read_b128 v[130:133], v21 offset:43120
	ds_read_b128 v[134:137], v21 offset:43136
	s_waitcnt lgkmcnt(14)
	v_pk_fma_f32 v[26:27], v[18:19], v[26:27], 0 op_sel_hi:[0,1,0]
	v_pk_fma_f32 v[26:27], v[20:21], v[30:31], v[26:27] op_sel_hi:[0,1,1]
	v_pk_fma_f32 v[28:29], v[18:19], v[28:29], 0 op_sel_hi:[0,1,0]
	v_pk_fma_f32 v[26:27], v[16:17], v[42:43], v[26:27] op_sel_hi:[0,1,1]
	v_pk_fma_f32 v[28:29], v[20:21], v[32:33], v[28:29] op_sel_hi:[0,1,1]
	s_waitcnt lgkmcnt(13)
	v_pk_fma_f32 v[26:27], v[22:23], v[46:47], v[26:27] op_sel_hi:[0,1,1]
	v_pk_fma_f32 v[28:29], v[16:17], v[44:45], v[28:29] op_sel_hi:[0,1,1]
	s_waitcnt lgkmcnt(12)
	v_pk_fma_f32 v[26:27], v[58:59], v[14:15], v[26:27] op_sel_hi:[1,0,1]
	v_pk_fma_f32 v[28:29], v[22:23], v[48:49], v[28:29] op_sel_hi:[0,1,1]
	s_waitcnt lgkmcnt(11)
	v_pk_fma_f32 v[26:27], v[62:63], v[24:25], v[26:27] op_sel_hi:[1,0,1]
	v_pk_fma_f32 v[28:29], v[60:61], v[14:15], v[28:29] op_sel_hi:[1,0,1]
	s_waitcnt lgkmcnt(10)
	v_pk_fma_f32 v[26:27], v[78:79], v[12:13], v[26:27] op_sel_hi:[1,0,1]
	v_cndmask_b32_e64 v15, 0, v13, s[6:7]
	v_sub_f32_e32 v15, v15, v26
	v_cndmask_b32_e32 v17, 0, v13, vcc
	v_sub_f32_e32 v17, v17, v27
	v_add_f32_dpp v15, v15, v15 quad_perm:[1,0,3,2] row_mask:0xf bank_mask:0xf bound_ctrl:1
	v_pk_fma_f32 v[28:29], v[64:65], v[24:25], v[28:29] op_sel_hi:[1,0,1]
	s_nop 0
	v_add_f32_dpp v15, v15, v15 quad_perm:[2,3,0,1] row_mask:0xf bank_mask:0xf bound_ctrl:1
	v_cndmask_b32_e64 v15, v13, v15, s[6:7]
	s_waitcnt lgkmcnt(9)
	v_fma_f32 v17, -v127, v15, v17
	v_pk_fma_f32 v[28:29], v[80:81], v[12:13], v[28:29] op_sel_hi:[1,0,1]
	s_nop 0
	v_add_f32_dpp v17, v17, v17 quad_perm:[1,0,3,2] row_mask:0xf bank_mask:0xf bound_ctrl:1
	s_nop 1
	v_add_f32_dpp v17, v17, v17 quad_perm:[2,3,0,1] row_mask:0xf bank_mask:0xf bound_ctrl:1
	v_cndmask_b32_e32 v15, v15, v17, vcc
	v_cndmask_b32_e64 v17, 0, v13, s[2:3]
	v_sub_f32_e32 v17, v17, v28
	v_fma_f32 v17, -v128, v15, v17
	v_cndmask_b32_e64 v13, 0, v13, s[4:5]
	v_sub_f32_e32 v13, v13, v29
	v_add_f32_dpp v17, v17, v17 quad_perm:[1,0,3,2] row_mask:0xf bank_mask:0xf bound_ctrl:1
	s_nop 1
	v_add_f32_dpp v17, v17, v17 quad_perm:[2,3,0,1] row_mask:0xf bank_mask:0xf bound_ctrl:1
	v_cndmask_b32_e64 v15, v15, v17, s[2:3]
	v_fma_f32 v13, -v129, v15, v13
	s_nop 1
	v_add_f32_dpp v13, v13, v13 quad_perm:[1,0,3,2] row_mask:0xf bank_mask:0xf bound_ctrl:1
	s_nop 1
	v_add_f32_dpp v13, v13, v13 quad_perm:[2,3,0,1] row_mask:0xf bank_mask:0xf bound_ctrl:1
	v_cndmask_b32_e64 v26, v15, v13, s[4:5]
	ds_read_b128 v[28:31], v21 offset:44096
	ds_read_b128 v[42:45], v21 offset:44112
	ds_read_b128 v[46:49], v21 offset:44128
	ds_read_b128 v[58:61], v21 offset:44144
	ds_read_b128 v[62:65], v21 offset:44160
	ds_read_b128 v[78:81], v21 offset:44176
	ds_read_b128 v[126:129], v21 offset:44192
	ds_read_b128 v[138:141], v21 offset:44208
	ds_read_b128 v[142:145], v21 offset:44224
	ds_read_b128 v[146:149], v21 offset:44240
	s_waitcnt lgkmcnt(14)
; #define LAS __attribute__((address_space(3)))
; #define WY_RDBLK(m_) do { _Pragma("unroll") for (int t_ = 0; t_ <= (m_); ++t_) LB[(m_) & 1][t_] = *(const LAS f32x4*)(lq + (m_) * WY_BS + 4 * t_); } while (0)
; __device__ __forceinline__ int wy_producer_task(const Ctx& c, int l, int tk, WyPre& P, unsigned* head) {
;     ...
;     {
;         f32x4 LB[2][16];
;         const LAS float* lq = LM + q4 * WY_QS;
;     ...
;         WY_RDBLK(0);
; #pragma unroll
;         for (int m = 0; m < 16; ++m) {
;             if (m + 1 < 16) WY_RDBLK(m + 1);
;             __builtin_amdgcn_sched_barrier(0);
;             f32x4 pre = (f32x4){0.f, 0.f, 0.f, 0.f};
; #pragma unroll
;             for (int t = 0; t < m; ++t) pre = LB[m & 1][t] * own[t] + pre;
; #pragma unroll
;             for (int rr = 0; rr < 4; ++rr) {
;                 float acc = ((q4 == rr) ? own[m] : 0.f) - pre[rr];
;                 if (rr > 0) acc = fmaf(-LB[m & 1][m][rr], own[m], acc);
;                 const float x = quad_sum(acc);
;                 own[m] = (q4 == rr) ? x : own[m]; }
;             __builtin_amdgcn_sched_barrier(0);
;         }
;     ...
;     }
	v_pk_fma_f32 v[32:33], v[18:19], v[34:35], 0 op_sel_hi:[0,1,0]
	v_pk_fma_f32 v[34:35], v[18:19], v[36:37], 0 op_sel_hi:[0,1,0]
	v_pk_fma_f32 v[32:33], v[20:21], v[38:39], v[32:33] op_sel_hi:[0,1,1]
	v_pk_fma_f32 v[34:35], v[20:21], v[40:41], v[34:35] op_sel_hi:[0,1,1]
	v_pk_fma_f32 v[32:33], v[16:17], v[50:51], v[32:33] op_sel_hi:[0,1,1]
	v_pk_fma_f32 v[34:35], v[16:17], v[52:53], v[34:35] op_sel_hi:[0,1,1]
	v_pk_fma_f32 v[32:33], v[22:23], v[54:55], v[32:33] op_sel_hi:[0,1,1]
	v_pk_fma_f32 v[34:35], v[22:23], v[56:57], v[34:35] op_sel_hi:[0,1,1]
	v_pk_fma_f32 v[32:33], v[14:15], v[66:67], v[32:33] op_sel_hi:[0,1,1]
	v_pk_fma_f32 v[34:35], v[14:15], v[68:69], v[34:35] op_sel_hi:[0,1,1]
	s_waitcnt lgkmcnt(13)
	v_pk_fma_f32 v[32:33], v[70:71], v[24:25], v[32:33] op_sel_hi:[1,0,1]
	v_pk_fma_f32 v[34:35], v[72:73], v[24:25], v[34:35] op_sel_hi:[1,0,1]
	s_waitcnt lgkmcnt(12)
	v_pk_fma_f32 v[32:33], v[74:75], v[12:13], v[32:33] op_sel_hi:[1,0,1]
	v_pk_fma_f32 v[34:35], v[76:77], v[12:13], v[34:35] op_sel_hi:[1,0,1]
	s_waitcnt lgkmcnt(11)
	v_pk_fma_f32 v[32:33], v[130:131], v[26:27], v[32:33] op_sel_hi:[1,0,1]
	v_cndmask_b32_e64 v13, 0, v10, s[6:7]
	v_sub_f32_e32 v13, v13, v32
	v_cndmask_b32_e32 v15, 0, v10, vcc
	v_sub_f32_e32 v15, v15, v33
	v_add_f32_dpp v13, v13, v13 quad_perm:[1,0,3,2] row_mask:0xf bank_mask:0xf bound_ctrl:1
	v_pk_fma_f32 v[34:35], v[132:133], v[26:27], v[34:35] op_sel_hi:[1,0,1]
	s_nop 0
	v_add_f32_dpp v13, v13, v13 quad_perm:[2,3,0,1] row_mask:0xf bank_mask:0xf bound_ctrl:1
	v_cndmask_b32_e64 v13, v10, v13, s[6:7]
	s_waitcnt lgkmcnt(10)
	v_fma_f32 v15, -v135, v13, v15
	s_nop 1
	v_add_f32_dpp v15, v15, v15 quad_perm:[1,0,3,2] row_mask:0xf bank_mask:0xf bound_ctrl:1
	s_nop 1
	v_add_f32_dpp v15, v15, v15 quad_perm:[2,3,0,1] row_mask:0xf bank_mask:0xf bound_ctrl:1
	v_cndmask_b32_e32 v13, v13, v15, vcc
	v_cndmask_b32_e64 v15, 0, v10, s[2:3]
	v_sub_f32_e32 v15, v15, v34
	v_fma_f32 v15, -v136, v13, v15
	v_cndmask_b32_e64 v10, 0, v10, s[4:5]
	v_sub_f32_e32 v10, v10, v35
	v_add_f32_dpp v15, v15, v15 quad_perm:[1,0,3,2] row_mask:0xf bank_mask:0xf bound_ctrl:1
	s_nop 1
	v_add_f32_dpp v15, v15, v15 quad_perm:[2,3,0,1] row_mask:0xf bank_mask:0xf bound_ctrl:1
	v_cndmask_b32_e64 v13, v13, v15, s[2:3]
	v_fma_f32 v10, -v137, v13, v10
	s_nop 1
	v_add_f32_dpp v10, v10, v10 quad_perm:[1,0,3,2] row_mask:0xf bank_mask:0xf bound_ctrl:1
	s_nop 1
	v_add_f32_dpp v10, v10, v10 quad_perm:[2,3,0,1] row_mask:0xf bank_mask:0xf bound_ctrl:1
	v_cndmask_b32_e64 v10, v13, v10, s[4:5]
	ds_read_b128 v[32:35], v21 offset:45184
	ds_read_b128 v[36:39], v21 offset:45200
	ds_read_b128 v[50:53], v21 offset:45216
	ds_read_b128 v[54:57], v21 offset:45232
	ds_read_b128 v[66:69], v21 offset:45248
	ds_read_b128 v[70:73], v21 offset:45264
	ds_read_b128 v[74:77], v21 offset:45280
	ds_read_b128 v[130:133], v21 offset:45296
	ds_read_b128 v[134:137], v21 offset:45312
	ds_read_b128 v[150:153], v21 offset:45328
	ds_read_b128 v[154:157], v21 offset:45344
	s_waitcnt lgkmcnt(14)
	v_pk_fma_f32 v[28:29], v[18:19], v[28:29], 0 op_sel_hi:[0,1,0]
	v_pk_fma_f32 v[28:29], v[20:21], v[42:43], v[28:29] op_sel_hi:[0,1,1]
	v_pk_fma_f32 v[30:31], v[18:19], v[30:31], 0 op_sel_hi:[0,1,0]
	v_pk_fma_f32 v[28:29], v[16:17], v[46:47], v[28:29] op_sel_hi:[0,1,1]
	v_pk_fma_f32 v[30:31], v[20:21], v[44:45], v[30:31] op_sel_hi:[0,1,1]
	v_pk_fma_f32 v[28:29], v[22:23], v[58:59], v[28:29] op_sel_hi:[0,1,1]
	v_pk_fma_f32 v[30:31], v[16:17], v[48:49], v[30:31] op_sel_hi:[0,1,1]
	v_pk_fma_f32 v[28:29], v[14:15], v[62:63], v[28:29] op_sel_hi:[0,1,1]
	v_pk_fma_f32 v[30:31], v[22:23], v[60:61], v[30:31] op_sel_hi:[0,1,1]
	v_pk_fma_f32 v[28:29], v[24:25], v[78:79], v[28:29] op_sel_hi:[0,1,1]
	v_pk_fma_f32 v[30:31], v[14:15], v[64:65], v[30:31] op_sel_hi:[0,1,1]
	v_pk_fma_f32 v[28:29], v[126:127], v[12:13], v[28:29] op_sel_hi:[1,0,1]
	v_pk_fma_f32 v[30:31], v[24:25], v[80:81], v[30:31] op_sel_hi:[0,1,1]
	s_waitcnt lgkmcnt(13)
	v_pk_fma_f32 v[28:29], v[138:139], v[26:27], v[28:29] op_sel_hi:[1,0,1]
	v_pk_fma_f32 v[30:31], v[128:129], v[12:13], v[30:31] op_sel_hi:[1,0,1]
	s_waitcnt lgkmcnt(12)
	v_pk_fma_f32 v[28:29], v[142:143], v[10:11], v[28:29] op_sel_hi:[1,0,1]
	v_cndmask_b32_e64 v13, 0, v11, s[6:7]
	v_sub_f32_e32 v13, v13, v28
	v_cndmask_b32_e32 v15, 0, v11, vcc
	v_sub_f32_e32 v15, v15, v29
	v_add_f32_dpp v13, v13, v13 quad_perm:[1,0,3,2] row_mask:0xf bank_mask:0xf bound_ctrl:1
	v_pk_fma_f32 v[30:31], v[140:141], v[26:27], v[30:31] op_sel_hi:[1,0,1]
	s_nop 0
	v_add_f32_dpp v13, v13, v13 quad_perm:[2,3,0,1] row_mask:0xf bank_mask:0xf bound_ctrl:1
	v_cndmask_b32_e64 v13, v11, v13, s[6:7]
	s_waitcnt lgkmcnt(11)
	v_fma_f32 v15, -v147, v13, v15
	v_pk_fma_f32 v[30:31], v[144:145], v[10:11], v[30:31] op_sel_hi:[1,0,1]
	s_nop 0
	v_add_f32_dpp v15, v15, v15 quad_perm:[1,0,3,2] row_mask:0xf bank_mask:0xf bound_ctrl:1
	s_nop 1
	v_add_f32_dpp v15, v15, v15 quad_perm:[2,3,0,1] row_mask:0xf bank_mask:0xf bound_ctrl:1
	v_cndmask_b32_e32 v13, v13, v15, vcc
	v_cndmask_b32_e64 v15, 0, v11, s[2:3]
	v_sub_f32_e32 v15, v15, v30
	v_fma_f32 v15, -v148, v13, v15
	v_cndmask_b32_e64 v11, 0, v11, s[4:5]
	v_sub_f32_e32 v11, v11, v31
	v_add_f32_dpp v15, v15, v15 quad_perm:[1,0,3,2] row_mask:0xf bank_mask:0xf bound_ctrl:1
	s_nop 1
	v_add_f32_dpp v15, v15, v15 quad_perm:[2,3,0,1] row_mask:0xf bank_mask:0xf bound_ctrl:1
	v_cndmask_b32_e64 v13, v13, v15, s[2:3]
	v_fma_f32 v11, -v149, v13, v11
	s_nop 1
	v_add_f32_dpp v11, v11, v11 quad_perm:[1,0,3,2] row_mask:0xf bank_mask:0xf bound_ctrl:1
	s_nop 1
	v_add_f32_dpp v11, v11, v11 quad_perm:[2,3,0,1] row_mask:0xf bank_mask:0xf bound_ctrl:1
	v_cndmask_b32_e64 v28, v13, v11, s[4:5]
	ds_read_b128 v[40:43], v21 offset:46272
	ds_read_b128 v[44:47], v21 offset:46288
	ds_read_b128 v[58:61], v21 offset:46304
	ds_read_b128 v[62:65], v21 offset:46320
	ds_read_b128 v[78:81], v21 offset:46336
	ds_read_b128 v[126:129], v21 offset:46352
	ds_read_b128 v[138:141], v21 offset:46368
	ds_read_b128 v[142:145], v21 offset:46384
	ds_read_b128 v[146:149], v21 offset:46400
	ds_read_b128 v[158:161], v21 offset:46416
	ds_read_b128 v[162:165], v21 offset:46432
	ds_read_b128 v[166:169], v21 offset:46448
	s_waitcnt lgkmcnt(14)
; #define LAS __attribute__((address_space(3)))
; #define WY_RDBLK(m_) do { _Pragma("unroll") for (int t_ = 0; t_ <= (m_); ++t_) LB[(m_) & 1][t_] = *(const LAS f32x4*)(lq + (m_) * WY_BS + 4 * t_); } while (0)
; __device__ __forceinline__ int wy_producer_task(const Ctx& c, int l, int tk, WyPre& P, unsigned* head) {
;     ...
;     {
;         f32x4 LB[2][16];
;         const LAS float* lq = LM + q4 * WY_QS;
;     ...
;         WY_RDBLK(0);
; #pragma unroll
;         for (int m = 0; m < 16; ++m) {
;             if (m + 1 < 16) WY_RDBLK(m + 1);
;             __builtin_amdgcn_sched_barrier(0);
;             f32x4 pre = (f32x4){0.f, 0.f, 0.f, 0.f};
; #pragma unroll
;             for (int t = 0; t < m; ++t) pre = LB[m & 1][t] * own[t] + pre;
; #pragma unroll
;             for (int rr = 0; rr < 4; ++rr) {
;                 float acc = ((q4 == rr) ? own[m] : 0.f) - pre[rr];
;                 if (rr > 0) acc = fmaf(-LB[m & 1][m][rr], own[m], acc);
;                 const float x = quad_sum(acc);
;                 own[m] = (q4 == rr) ? x : own[m]; }
;             __builtin_amdgcn_sched_barrier(0);
;         }
;     ...
;     }
	v_pk_fma_f32 v[30:31], v[18:19], v[32:33], 0 op_sel_hi:[0,1,0]
	v_pk_fma_f32 v[32:33], v[18:19], v[34:35], 0 op_sel_hi:[0,1,0]
	v_pk_fma_f32 v[30:31], v[20:21], v[36:37], v[30:31] op_sel_hi:[0,1,1]
	v_pk_fma_f32 v[32:33], v[20:21], v[38:39], v[32:33] op_sel_hi:[0,1,1]
	v_pk_fma_f32 v[30:31], v[16:17], v[50:51], v[30:31] op_sel_hi:[0,1,1]
	v_pk_fma_f32 v[32:33], v[16:17], v[52:53], v[32:33] op_sel_hi:[0,1,1]
	v_pk_fma_f32 v[30:31], v[22:23], v[54:55], v[30:31] op_sel_hi:[0,1,1]
	v_pk_fma_f32 v[32:33], v[22:23], v[56:57], v[32:33] op_sel_hi:[0,1,1]
	v_pk_fma_f32 v[30:31], v[14:15], v[66:67], v[30:31] op_sel_hi:[0,1,1]
	v_pk_fma_f32 v[32:33], v[14:15], v[68:69], v[32:33] op_sel_hi:[0,1,1]
	v_pk_fma_f32 v[30:31], v[24:25], v[70:71], v[30:31] op_sel_hi:[0,1,1]
	v_pk_fma_f32 v[32:33], v[24:25], v[72:73], v[32:33] op_sel_hi:[0,1,1]
	v_pk_fma_f32 v[30:31], v[12:13], v[74:75], v[30:31] op_sel_hi:[0,1,1]
	v_pk_fma_f32 v[32:33], v[12:13], v[76:77], v[32:33] op_sel_hi:[0,1,1]
	v_pk_fma_f32 v[30:31], v[130:131], v[26:27], v[30:31] op_sel_hi:[1,0,1]
	v_pk_fma_f32 v[32:33], v[132:133], v[26:27], v[32:33] op_sel_hi:[1,0,1]
	v_pk_fma_f32 v[30:31], v[134:135], v[10:11], v[30:31] op_sel_hi:[1,0,1]
	v_pk_fma_f32 v[32:33], v[136:137], v[10:11], v[32:33] op_sel_hi:[1,0,1]
	s_waitcnt lgkmcnt(13)
	v_pk_fma_f32 v[30:31], v[150:151], v[28:29], v[30:31] op_sel_hi:[1,0,1]
	v_cndmask_b32_e64 v11, 0, v8, s[6:7]
	v_sub_f32_e32 v11, v11, v30
	v_cndmask_b32_e32 v13, 0, v8, vcc
	v_sub_f32_e32 v13, v13, v31
	v_add_f32_dpp v11, v11, v11 quad_perm:[1,0,3,2] row_mask:0xf bank_mask:0xf bound_ctrl:1
	v_pk_fma_f32 v[32:33], v[152:153], v[28:29], v[32:33] op_sel_hi:[1,0,1]
	s_nop 0
	v_add_f32_dpp v11, v11, v11 quad_perm:[2,3,0,1] row_mask:0xf bank_mask:0xf bound_ctrl:1
	v_cndmask_b32_e64 v11, v8, v11, s[6:7]
	s_waitcnt lgkmcnt(12)
	v_fma_f32 v13, -v155, v11, v13
	s_nop 1
	v_add_f32_dpp v13, v13, v13 quad_perm:[1,0,3,2] row_mask:0xf bank_mask:0xf bound_ctrl:1
	s_nop 1
	v_add_f32_dpp v13, v13, v13 quad_perm:[2,3,0,1] row_mask:0xf bank_mask:0xf bound_ctrl:1
	v_cndmask_b32_e32 v11, v11, v13, vcc
	v_cndmask_b32_e64 v13, 0, v8, s[2:3]
	v_sub_f32_e32 v13, v13, v32
	v_fma_f32 v13, -v156, v11, v13
	v_cndmask_b32_e64 v8, 0, v8, s[4:5]
	v_sub_f32_e32 v8, v8, v33
	v_add_f32_dpp v13, v13, v13 quad_perm:[1,0,3,2] row_mask:0xf bank_mask:0xf bound_ctrl:1
	s_nop 1
	v_add_f32_dpp v13, v13, v13 quad_perm:[2,3,0,1] row_mask:0xf bank_mask:0xf bound_ctrl:1
	v_cndmask_b32_e64 v11, v11, v13, s[2:3]
	v_fma_f32 v8, -v157, v11, v8
	s_nop 1
	v_add_f32_dpp v8, v8, v8 quad_perm:[1,0,3,2] row_mask:0xf bank_mask:0xf bound_ctrl:1
	s_nop 1
	v_add_f32_dpp v8, v8, v8 quad_perm:[2,3,0,1] row_mask:0xf bank_mask:0xf bound_ctrl:1
	v_cndmask_b32_e64 v8, v11, v8, s[4:5]
	ds_read_b128 v[32:35], v21 offset:47360
	ds_read_b128 v[36:39], v21 offset:47376
	ds_read_b128 v[48:51], v21 offset:47392
	ds_read_b128 v[52:55], v21 offset:47408
	ds_read_b128 v[66:69], v21 offset:47424
	ds_read_b128 v[70:73], v21 offset:47440
	ds_read_b128 v[74:77], v21 offset:47456
	ds_read_b128 v[130:133], v21 offset:47472
	ds_read_b128 v[134:137], v21 offset:47488
	ds_read_b128 v[150:153], v21 offset:47504
	ds_read_b128 v[154:157], v21 offset:47520
	ds_read_b128 v[170:173], v21 offset:47536
	ds_read_b128 v[174:177], v21 offset:47552
	s_waitcnt lgkmcnt(14)
	v_pk_fma_f32 v[40:41], v[18:19], v[40:41], 0 op_sel_hi:[0,1,0]
	v_pk_fma_f32 v[40:41], v[20:21], v[44:45], v[40:41] op_sel_hi:[0,1,1]
	v_pk_fma_f32 v[30:31], v[18:19], v[42:43], 0 op_sel_hi:[0,1,0]
	v_pk_fma_f32 v[40:41], v[16:17], v[58:59], v[40:41] op_sel_hi:[0,1,1]
	v_pk_fma_f32 v[30:31], v[20:21], v[46:47], v[30:31] op_sel_hi:[0,1,1]
	v_pk_fma_f32 v[40:41], v[22:23], v[62:63], v[40:41] op_sel_hi:[0,1,1]
	v_pk_fma_f32 v[30:31], v[16:17], v[60:61], v[30:31] op_sel_hi:[0,1,1]
	v_pk_fma_f32 v[40:41], v[14:15], v[78:79], v[40:41] op_sel_hi:[0,1,1]
	v_pk_fma_f32 v[30:31], v[22:23], v[64:65], v[30:31] op_sel_hi:[0,1,1]
	v_pk_fma_f32 v[40:41], v[24:25], v[126:127], v[40:41] op_sel_hi:[0,1,1]
	v_pk_fma_f32 v[30:31], v[14:15], v[80:81], v[30:31] op_sel_hi:[0,1,1]
	v_pk_fma_f32 v[40:41], v[12:13], v[138:139], v[40:41] op_sel_hi:[0,1,1]
	v_pk_fma_f32 v[30:31], v[24:25], v[128:129], v[30:31] op_sel_hi:[0,1,1]
	v_pk_fma_f32 v[40:41], v[26:27], v[142:143], v[40:41] op_sel_hi:[0,1,1]
	v_pk_fma_f32 v[30:31], v[12:13], v[140:141], v[30:31] op_sel_hi:[0,1,1]
	v_pk_fma_f32 v[40:41], v[146:147], v[10:11], v[40:41] op_sel_hi:[1,0,1]
	v_pk_fma_f32 v[30:31], v[26:27], v[144:145], v[30:31] op_sel_hi:[0,1,1]
	v_pk_fma_f32 v[40:41], v[158:159], v[28:29], v[40:41] op_sel_hi:[1,0,1]
	v_pk_fma_f32 v[30:31], v[148:149], v[10:11], v[30:31] op_sel_hi:[1,0,1]
	v_pk_fma_f32 v[40:41], v[162:163], v[8:9], v[40:41] op_sel_hi:[1,0,1]
	v_cndmask_b32_e64 v11, 0, v9, s[6:7]
	v_sub_f32_e32 v11, v11, v40
	v_cndmask_b32_e32 v13, 0, v9, vcc
	v_sub_f32_e32 v13, v13, v41
	v_add_f32_dpp v11, v11, v11 quad_perm:[1,0,3,2] row_mask:0xf bank_mask:0xf bound_ctrl:1
	v_pk_fma_f32 v[30:31], v[160:161], v[28:29], v[30:31] op_sel_hi:[1,0,1]
	s_nop 0
	v_add_f32_dpp v11, v11, v11 quad_perm:[2,3,0,1] row_mask:0xf bank_mask:0xf bound_ctrl:1
	v_cndmask_b32_e64 v11, v9, v11, s[6:7]
	s_waitcnt lgkmcnt(13)
; #define WY_RDBLK(m_) do { _Pragma("unroll") for (int t_ = 0; t_ <= (m_); ++t_) LB[(m_) & 1][t_] = *(const LAS f32x4*)(lq + (m_) * WY_BS + 4 * t_); } while (0)
; __device__ __forceinline__ int wy_producer_task(const Ctx& c, int l, int tk, WyPre& P, unsigned* head) {
;     ...
;         for (int m = 0; m < 16; ++m) {
;             if (m + 1 < 16) WY_RDBLK(m + 1);
;             __builtin_amdgcn_sched_barrier(0);
;             f32x4 pre = (f32x4){0.f, 0.f, 0.f, 0.f};
; #pragma unroll
;             for (int t = 0; t < m; ++t) pre = LB[m & 1][t] * own[t] + pre;
; #pragma unroll
;             for (int rr = 0; rr < 4; ++rr) {
;                 float acc = ((q4 == rr) ? own[m] : 0.f) - pre[rr];
;                 if (rr > 0) acc = fmaf(-LB[m & 1][m][rr], own[m], acc);
;                 const float x = quad_sum(acc);
;                 own[m] = (q4 == rr) ? x : own[m]; }
;             __builtin_amdgcn_sched_barrier(0);
;         }
	v_fma_f32 v13, -v167, v11, v13
	v_pk_fma_f32 v[30:31], v[164:165], v[8:9], v[30:31] op_sel_hi:[1,0,1]
	s_nop 0
	v_add_f32_dpp v13, v13, v13 quad_perm:[1,0,3,2] row_mask:0xf bank_mask:0xf bound_ctrl:1
	s_nop 1
	v_add_f32_dpp v13, v13, v13 quad_perm:[2,3,0,1] row_mask:0xf bank_mask:0xf bound_ctrl:1
	v_cndmask_b32_e32 v11, v11, v13, vcc
	v_cndmask_b32_e64 v13, 0, v9, s[2:3]
	v_sub_f32_e32 v13, v13, v30
	v_fma_f32 v13, -v168, v11, v13
	v_cndmask_b32_e64 v9, 0, v9, s[4:5]
	v_sub_f32_e32 v9, v9, v31
	v_add_f32_dpp v13, v13, v13 quad_perm:[1,0,3,2] row_mask:0xf bank_mask:0xf bound_ctrl:1
	s_nop 1
	v_add_f32_dpp v13, v13, v13 quad_perm:[2,3,0,1] row_mask:0xf bank_mask:0xf bound_ctrl:1
	v_cndmask_b32_e64 v11, v11, v13, s[2:3]
	v_fma_f32 v9, -v169, v11, v9
	s_nop 1
	v_add_f32_dpp v9, v9, v9 quad_perm:[1,0,3,2] row_mask:0xf bank_mask:0xf bound_ctrl:1
	s_nop 1
	v_add_f32_dpp v9, v9, v9 quad_perm:[2,3,0,1] row_mask:0xf bank_mask:0xf bound_ctrl:1
	v_cndmask_b32_e64 v30, v11, v9, s[4:5]
	ds_read_b128 v[40:43], v21 offset:48448
	ds_read_b128 v[44:47], v21 offset:48464
	ds_read_b128 v[56:59], v21 offset:48480
	ds_read_b128 v[60:63], v21 offset:48496
	ds_read_b128 v[78:81], v21 offset:48512
	ds_read_b128 v[126:129], v21 offset:48528
	ds_read_b128 v[138:141], v21 offset:48544
	ds_read_b128 v[142:145], v21 offset:48560
	ds_read_b128 v[146:149], v21 offset:48576
	ds_read_b128 v[158:161], v21 offset:48592
	ds_read_b128 v[162:165], v21 offset:48608
	ds_read_b128 v[166:169], v21 offset:48624
	ds_read_b128 v[178:181], v21 offset:48640
	ds_read_b128 v[182:185], v21 offset:48656
	s_waitcnt lgkmcnt(14)
	v_pk_fma_f32 v[32:33], v[18:19], v[32:33], 0 op_sel_hi:[0,1,0]
	v_pk_fma_f32 v[34:35], v[18:19], v[34:35], 0 op_sel_hi:[0,1,0]
	v_pk_fma_f32 v[32:33], v[20:21], v[36:37], v[32:33] op_sel_hi:[0,1,1]
	v_pk_fma_f32 v[34:35], v[20:21], v[38:39], v[34:35] op_sel_hi:[0,1,1]
	v_pk_fma_f32 v[32:33], v[16:17], v[48:49], v[32:33] op_sel_hi:[0,1,1]
	v_pk_fma_f32 v[34:35], v[16:17], v[50:51], v[34:35] op_sel_hi:[0,1,1]
	v_pk_fma_f32 v[32:33], v[22:23], v[52:53], v[32:33] op_sel_hi:[0,1,1]
	v_pk_fma_f32 v[34:35], v[22:23], v[54:55], v[34:35] op_sel_hi:[0,1,1]
	v_pk_fma_f32 v[32:33], v[14:15], v[66:67], v[32:33] op_sel_hi:[0,1,1]
	v_pk_fma_f32 v[34:35], v[14:15], v[68:69], v[34:35] op_sel_hi:[0,1,1]
	v_pk_fma_f32 v[32:33], v[24:25], v[70:71], v[32:33] op_sel_hi:[0,1,1]
	v_pk_fma_f32 v[34:35], v[24:25], v[72:73], v[34:35] op_sel_hi:[0,1,1]
	v_pk_fma_f32 v[32:33], v[12:13], v[74:75], v[32:33] op_sel_hi:[0,1,1]
	v_pk_fma_f32 v[34:35], v[12:13], v[76:77], v[34:35] op_sel_hi:[0,1,1]
	v_pk_fma_f32 v[32:33], v[26:27], v[130:131], v[32:33] op_sel_hi:[0,1,1]
	v_pk_fma_f32 v[34:35], v[26:27], v[132:133], v[34:35] op_sel_hi:[0,1,1]
	v_pk_fma_f32 v[32:33], v[10:11], v[134:135], v[32:33] op_sel_hi:[0,1,1]
	v_pk_fma_f32 v[34:35], v[10:11], v[136:137], v[34:35] op_sel_hi:[0,1,1]
	v_pk_fma_f32 v[32:33], v[150:151], v[28:29], v[32:33] op_sel_hi:[1,0,1]
	v_pk_fma_f32 v[34:35], v[152:153], v[28:29], v[34:35] op_sel_hi:[1,0,1]
	v_pk_fma_f32 v[32:33], v[154:155], v[8:9], v[32:33] op_sel_hi:[1,0,1]
	v_pk_fma_f32 v[34:35], v[156:157], v[8:9], v[34:35] op_sel_hi:[1,0,1]
	v_pk_fma_f32 v[32:33], v[170:171], v[30:31], v[32:33] op_sel_hi:[1,0,1]
	v_cndmask_b32_e64 v9, 0, v6, s[6:7]
	v_sub_f32_e32 v9, v9, v32
	v_cndmask_b32_e32 v11, 0, v6, vcc
	v_sub_f32_e32 v11, v11, v33
	v_add_f32_dpp v9, v9, v9 quad_perm:[1,0,3,2] row_mask:0xf bank_mask:0xf bound_ctrl:1
	v_pk_fma_f32 v[34:35], v[172:173], v[30:31], v[34:35] op_sel_hi:[1,0,1]
	s_nop 0
	v_add_f32_dpp v9, v9, v9 quad_perm:[2,3,0,1] row_mask:0xf bank_mask:0xf bound_ctrl:1
	v_cndmask_b32_e64 v9, v6, v9, s[6:7]
	v_fma_f32 v11, -v175, v9, v11
	s_nop 1
	v_add_f32_dpp v11, v11, v11 quad_perm:[1,0,3,2] row_mask:0xf bank_mask:0xf bound_ctrl:1
	s_nop 1
	v_add_f32_dpp v11, v11, v11 quad_perm:[2,3,0,1] row_mask:0xf bank_mask:0xf bound_ctrl:1
	v_cndmask_b32_e32 v9, v9, v11, vcc
	v_cndmask_b32_e64 v11, 0, v6, s[2:3]
	v_sub_f32_e32 v11, v11, v34
	v_fma_f32 v11, -v176, v9, v11
	v_cndmask_b32_e64 v6, 0, v6, s[4:5]
	v_sub_f32_e32 v6, v6, v35
	v_add_f32_dpp v11, v11, v11 quad_perm:[1,0,3,2] row_mask:0xf bank_mask:0xf bound_ctrl:1
	s_nop 1
	v_add_f32_dpp v11, v11, v11 quad_perm:[2,3,0,1] row_mask:0xf bank_mask:0xf bound_ctrl:1
	v_cndmask_b32_e64 v9, v9, v11, s[2:3]
	v_fma_f32 v6, -v177, v9, v6
	s_nop 1
	v_add_f32_dpp v6, v6, v6 quad_perm:[1,0,3,2] row_mask:0xf bank_mask:0xf bound_ctrl:1
	s_nop 1
	v_add_f32_dpp v6, v6, v6 quad_perm:[2,3,0,1] row_mask:0xf bank_mask:0xf bound_ctrl:1
	v_cndmask_b32_e64 v6, v9, v6, s[4:5]
	ds_read_b128 v[34:37], v21 offset:49536
	ds_read_b128 v[48:51], v21 offset:49552
	ds_read_b128 v[52:55], v21 offset:49568
	ds_read_b128 v[64:67], v21 offset:49584
	ds_read_b128 v[68:71], v21 offset:49600
	ds_read_b128 v[72:75], v21 offset:49616
	ds_read_b128 v[130:133], v21 offset:49632
	ds_read_b128 v[134:137], v21 offset:49648
	ds_read_b128 v[150:153], v21 offset:49664
	ds_read_b128 v[154:157], v21 offset:49680
	ds_read_b128 v[170:173], v21 offset:49696
	ds_read_b128 v[174:177], v21 offset:49712
	ds_read_b128 v[186:189], v21 offset:49728
	ds_read_b128 v[190:193], v21 offset:49744
	ds_read_b128 v[194:197], v21 offset:49760
	s_waitcnt lgkmcnt(14)
; #define WY_RDBLK(m_) do { _Pragma("unroll") for (int t_ = 0; t_ <= (m_); ++t_) LB[(m_) & 1][t_] = *(const LAS f32x4*)(lq + (m_) * WY_BS + 4 * t_); } while (0)
; __device__ __forceinline__ int wy_producer_task(const Ctx& c, int l, int tk, WyPre& P, unsigned* head) {
;     ...
;         for (int m = 0; m < 16; ++m) {
;             if (m + 1 < 16) WY_RDBLK(m + 1);
;             __builtin_amdgcn_sched_barrier(0);
;             f32x4 pre = (f32x4){0.f, 0.f, 0.f, 0.f};
; #pragma unroll
;             for (int t = 0; t < m; ++t) pre = LB[m & 1][t] * own[t] + pre;
; #pragma unroll
;             for (int rr = 0; rr < 4; ++rr) {
;                 float acc = ((q4 == rr) ? own[m] : 0.f) - pre[rr];
;                 if (rr > 0) acc = fmaf(-LB[m & 1][m][rr], own[m], acc);
;                 const float x = quad_sum(acc);
;                 own[m] = (q4 == rr) ? x : own[m]; }
;             __builtin_amdgcn_sched_barrier(0);
;         }
	v_pk_fma_f32 v[38:39], v[18:19], v[40:41], 0 op_sel_hi:[0,1,0]
	v_pk_fma_f32 v[38:39], v[20:21], v[44:45], v[38:39] op_sel_hi:[0,1,1]
	v_pk_fma_f32 v[32:33], v[18:19], v[42:43], 0 op_sel_hi:[0,1,0]
	v_pk_fma_f32 v[38:39], v[16:17], v[56:57], v[38:39] op_sel_hi:[0,1,1]
	v_pk_fma_f32 v[32:33], v[20:21], v[46:47], v[32:33] op_sel_hi:[0,1,1]
	v_pk_fma_f32 v[38:39], v[22:23], v[60:61], v[38:39] op_sel_hi:[0,1,1]
	v_pk_fma_f32 v[32:33], v[16:17], v[58:59], v[32:33] op_sel_hi:[0,1,1]
	v_pk_fma_f32 v[38:39], v[14:15], v[78:79], v[38:39] op_sel_hi:[0,1,1]
	v_pk_fma_f32 v[32:33], v[22:23], v[62:63], v[32:33] op_sel_hi:[0,1,1]
	v_pk_fma_f32 v[38:39], v[24:25], v[126:127], v[38:39] op_sel_hi:[0,1,1]
	v_pk_fma_f32 v[32:33], v[14:15], v[80:81], v[32:33] op_sel_hi:[0,1,1]
	v_pk_fma_f32 v[38:39], v[12:13], v[138:139], v[38:39] op_sel_hi:[0,1,1]
	v_pk_fma_f32 v[32:33], v[24:25], v[128:129], v[32:33] op_sel_hi:[0,1,1]
	v_pk_fma_f32 v[38:39], v[26:27], v[142:143], v[38:39] op_sel_hi:[0,1,1]
	v_pk_fma_f32 v[32:33], v[12:13], v[140:141], v[32:33] op_sel_hi:[0,1,1]
	v_pk_fma_f32 v[38:39], v[10:11], v[146:147], v[38:39] op_sel_hi:[0,1,1]
	v_pk_fma_f32 v[32:33], v[26:27], v[144:145], v[32:33] op_sel_hi:[0,1,1]
	v_pk_fma_f32 v[38:39], v[28:29], v[158:159], v[38:39] op_sel_hi:[0,1,1]
	v_pk_fma_f32 v[32:33], v[10:11], v[148:149], v[32:33] op_sel_hi:[0,1,1]
	v_pk_fma_f32 v[38:39], v[162:163], v[8:9], v[38:39] op_sel_hi:[1,0,1]
	v_pk_fma_f32 v[32:33], v[28:29], v[160:161], v[32:33] op_sel_hi:[0,1,1]
	v_pk_fma_f32 v[38:39], v[166:167], v[30:31], v[38:39] op_sel_hi:[1,0,1]
	v_pk_fma_f32 v[32:33], v[164:165], v[8:9], v[32:33] op_sel_hi:[1,0,1]
	v_pk_fma_f32 v[38:39], v[178:179], v[6:7], v[38:39] op_sel_hi:[1,0,1]
	v_cndmask_b32_e64 v9, 0, v7, s[6:7]
	v_sub_f32_e32 v9, v9, v38
	v_cndmask_b32_e32 v11, 0, v7, vcc
	v_sub_f32_e32 v11, v11, v39
	v_add_f32_dpp v9, v9, v9 quad_perm:[1,0,3,2] row_mask:0xf bank_mask:0xf bound_ctrl:1
	v_pk_fma_f32 v[32:33], v[168:169], v[30:31], v[32:33] op_sel_hi:[1,0,1]
	s_nop 0
	v_add_f32_dpp v9, v9, v9 quad_perm:[2,3,0,1] row_mask:0xf bank_mask:0xf bound_ctrl:1
	v_cndmask_b32_e64 v9, v7, v9, s[6:7]
	v_fma_f32 v11, -v183, v9, v11
	v_pk_fma_f32 v[32:33], v[180:181], v[6:7], v[32:33] op_sel_hi:[1,0,1]
	s_nop 0
	v_add_f32_dpp v11, v11, v11 quad_perm:[1,0,3,2] row_mask:0xf bank_mask:0xf bound_ctrl:1
	s_nop 1
	v_add_f32_dpp v11, v11, v11 quad_perm:[2,3,0,1] row_mask:0xf bank_mask:0xf bound_ctrl:1
	v_cndmask_b32_e32 v9, v9, v11, vcc
	v_cndmask_b32_e64 v11, 0, v7, s[2:3]
	v_sub_f32_e32 v11, v11, v32
	v_fma_f32 v11, -v184, v9, v11
	v_cndmask_b32_e64 v7, 0, v7, s[4:5]
	v_sub_f32_e32 v7, v7, v33
	v_add_f32_dpp v11, v11, v11 quad_perm:[1,0,3,2] row_mask:0xf bank_mask:0xf bound_ctrl:1
	s_nop 1
	v_add_f32_dpp v11, v11, v11 quad_perm:[2,3,0,1] row_mask:0xf bank_mask:0xf bound_ctrl:1
	v_cndmask_b32_e64 v9, v9, v11, s[2:3]
	v_fma_f32 v7, -v185, v9, v7
	s_nop 1
	v_add_f32_dpp v7, v7, v7 quad_perm:[1,0,3,2] row_mask:0xf bank_mask:0xf bound_ctrl:1
	s_nop 1
	v_add_f32_dpp v7, v7, v7 quad_perm:[2,3,0,1] row_mask:0xf bank_mask:0xf bound_ctrl:1
	v_cndmask_b32_e64 v32, v9, v7, s[4:5]
	ds_read_b128 v[38:41], v21 offset:50624
	ds_read_b128 v[42:45], v21 offset:50640
	ds_read_b128 v[56:59], v21 offset:50656
	ds_read_b128 v[60:63], v21 offset:50672
	ds_read_b128 v[76:79], v21 offset:50688
	ds_read_b128 v[126:129], v21 offset:50704
	ds_read_b128 v[138:141], v21 offset:50720
	ds_read_b128 v[142:145], v21 offset:50736
	ds_read_b128 v[146:149], v21 offset:50752
	ds_read_b128 v[158:161], v21 offset:50768
	ds_read_b128 v[162:165], v21 offset:50784
	ds_read_b128 v[166:169], v21 offset:50800
	ds_read_b128 v[178:181], v21 offset:50816
	ds_read_b128 v[182:185], v21 offset:50832
	ds_read_b128 v[198:201], v21 offset:50848
	ds_read_b128 v[202:205], v21 offset:50864
	v_pk_fma_f32 v[34:35], v[18:19], v[34:35], 0 op_sel_hi:[0,1,0]
	v_pk_fma_f32 v[36:37], v[18:19], v[36:37], 0 op_sel_hi:[0,1,0]
	s_waitcnt lgkmcnt(14)
	v_pk_fma_f32 v[34:35], v[20:21], v[48:49], v[34:35] op_sel_hi:[0,1,1]
	v_pk_fma_f32 v[36:37], v[20:21], v[50:51], v[36:37] op_sel_hi:[0,1,1]
	v_pk_fma_f32 v[34:35], v[16:17], v[52:53], v[34:35] op_sel_hi:[0,1,1]
	v_pk_fma_f32 v[36:37], v[16:17], v[54:55], v[36:37] op_sel_hi:[0,1,1]
	v_pk_fma_f32 v[34:35], v[22:23], v[64:65], v[34:35] op_sel_hi:[0,1,1]
	v_pk_fma_f32 v[36:37], v[22:23], v[66:67], v[36:37] op_sel_hi:[0,1,1]
	v_pk_fma_f32 v[34:35], v[14:15], v[68:69], v[34:35] op_sel_hi:[0,1,1]
	v_pk_fma_f32 v[36:37], v[14:15], v[70:71], v[36:37] op_sel_hi:[0,1,1]
	v_pk_fma_f32 v[34:35], v[24:25], v[72:73], v[34:35] op_sel_hi:[0,1,1]
	v_pk_fma_f32 v[36:37], v[24:25], v[74:75], v[36:37] op_sel_hi:[0,1,1]
	v_pk_fma_f32 v[34:35], v[12:13], v[130:131], v[34:35] op_sel_hi:[0,1,1]
	v_pk_fma_f32 v[36:37], v[12:13], v[132:133], v[36:37] op_sel_hi:[0,1,1]
	v_pk_fma_f32 v[34:35], v[26:27], v[134:135], v[34:35] op_sel_hi:[0,1,1]
	v_pk_fma_f32 v[36:37], v[26:27], v[136:137], v[36:37] op_sel_hi:[0,1,1]
	v_pk_fma_f32 v[34:35], v[10:11], v[150:151], v[34:35] op_sel_hi:[0,1,1]
	v_pk_fma_f32 v[36:37], v[10:11], v[152:153], v[36:37] op_sel_hi:[0,1,1]
	v_pk_fma_f32 v[34:35], v[28:29], v[154:155], v[34:35] op_sel_hi:[0,1,1]
	v_pk_fma_f32 v[36:37], v[28:29], v[156:157], v[36:37] op_sel_hi:[0,1,1]
	v_pk_fma_f32 v[34:35], v[8:9], v[170:171], v[34:35] op_sel_hi:[0,1,1]
	v_pk_fma_f32 v[36:37], v[8:9], v[172:173], v[36:37] op_sel_hi:[0,1,1]
	v_pk_fma_f32 v[34:35], v[174:175], v[30:31], v[34:35] op_sel_hi:[1,0,1]
	v_pk_fma_f32 v[36:37], v[176:177], v[30:31], v[36:37] op_sel_hi:[1,0,1]
	v_pk_fma_f32 v[34:35], v[186:187], v[6:7], v[34:35] op_sel_hi:[1,0,1]
	v_pk_fma_f32 v[36:37], v[188:189], v[6:7], v[36:37] op_sel_hi:[1,0,1]
; __device__ __forceinline__ float bf2f(bf16 v) { return __uint_as_float(((unsigned)v) << 16); }
; #define WY_RDBLK(m_) do { _Pragma("unroll") for (int t_ = 0; t_ <= (m_); ++t_) LB[(m_) & 1][t_] = *(const LAS f32x4*)(lq + (m_) * WY_BS + 4 * t_); } while (0)
; __device__ __forceinline__ int wy_producer_task(const Ctx& c, int l, int tk, WyPre& P, unsigned* head) {
;     ...
;     for (int j = 0; j < 3; ++j) { float xv[11];
; #pragma unroll
;         for (int r = 0; r < 11; ++r) xv[r] = bf2f((bf16)P.hx[j][r]);
;     ...
;         for (int m = 0; m < 16; ++m) {
;             if (m + 1 < 16) WY_RDBLK(m + 1);
;             __builtin_amdgcn_sched_barrier(0);
;             f32x4 pre = (f32x4){0.f, 0.f, 0.f, 0.f};
; #pragma unroll
;             for (int t = 0; t < m; ++t) pre = LB[m & 1][t] * own[t] + pre;
; #pragma unroll
;             for (int rr = 0; rr < 4; ++rr) {
;                 float acc = ((q4 == rr) ? own[m] : 0.f) - pre[rr];
;                 if (rr > 0) acc = fmaf(-LB[m & 1][m][rr], own[m], acc);
;                 const float x = quad_sum(acc);
;                 own[m] = (q4 == rr) ? x : own[m]; }
;             __builtin_amdgcn_sched_barrier(0);
;         }
;     ...
;     }
;     if (wid < 4) { float* vo = (float*)(AWS + WS_VAL) + (size_t)tk * 4096 + 16 * wid + cc;
; #pragma unroll
;         for (int t = 0; t < 16; ++t) vo[(4 * t + q4) * 64] = own[t]; }
;     else {
; #pragma unroll
;         for (int t = 0; t < 16; ++t) KT[(4 * t + q4) * 65 + 16 * (wid - 4) + cc] = own[t]; }
	v_pk_fma_f32 v[34:35], v[190:191], v[32:33], v[34:35] op_sel_hi:[1,0,1]
	v_cndmask_b32_e64 v7, 0, v4, s[6:7]
	v_sub_f32_e32 v7, v7, v34
	v_cndmask_b32_e32 v9, 0, v4, vcc
	v_sub_f32_e32 v9, v9, v35
	v_add_f32_dpp v7, v7, v7 quad_perm:[1,0,3,2] row_mask:0xf bank_mask:0xf bound_ctrl:1
	v_pk_fma_f32 v[36:37], v[192:193], v[32:33], v[36:37] op_sel_hi:[1,0,1]
	s_nop 0
	v_add_f32_dpp v7, v7, v7 quad_perm:[2,3,0,1] row_mask:0xf bank_mask:0xf bound_ctrl:1
	v_cndmask_b32_e64 v7, v4, v7, s[6:7]
	v_fma_f32 v9, -v195, v7, v9
	s_nop 1
	v_add_f32_dpp v9, v9, v9 quad_perm:[1,0,3,2] row_mask:0xf bank_mask:0xf bound_ctrl:1
	s_nop 1
	v_add_f32_dpp v9, v9, v9 quad_perm:[2,3,0,1] row_mask:0xf bank_mask:0xf bound_ctrl:1
	v_cndmask_b32_e32 v7, v7, v9, vcc
	v_cndmask_b32_e64 v9, 0, v4, s[2:3]
	v_sub_f32_e32 v9, v9, v36
	v_fma_f32 v9, -v196, v7, v9
	v_cndmask_b32_e64 v4, 0, v4, s[4:5]
	v_sub_f32_e32 v4, v4, v37
	v_add_f32_dpp v9, v9, v9 quad_perm:[1,0,3,2] row_mask:0xf bank_mask:0xf bound_ctrl:1
	s_nop 1
	v_add_f32_dpp v9, v9, v9 quad_perm:[2,3,0,1] row_mask:0xf bank_mask:0xf bound_ctrl:1
	v_cndmask_b32_e64 v7, v7, v9, s[2:3]
	v_fma_f32 v4, -v197, v7, v4
	s_nop 1
	v_add_f32_dpp v4, v4, v4 quad_perm:[1,0,3,2] row_mask:0xf bank_mask:0xf bound_ctrl:1
	s_nop 1
	v_add_f32_dpp v4, v4, v4 quad_perm:[2,3,0,1] row_mask:0xf bank_mask:0xf bound_ctrl:1
	v_cndmask_b32_e64 v4, v7, v4, s[4:5]
	v_pk_fma_f32 v[36:37], v[18:19], v[38:39], 0 op_sel_hi:[0,1,0]
	v_pk_fma_f32 v[36:37], v[20:21], v[42:43], v[36:37] op_sel_hi:[0,1,1]
	v_pk_fma_f32 v[34:35], v[18:19], v[40:41], 0 op_sel_hi:[0,1,0]
	s_waitcnt lgkmcnt(13)
	v_pk_fma_f32 v[36:37], v[16:17], v[56:57], v[36:37] op_sel_hi:[0,1,1]
	v_pk_fma_f32 v[34:35], v[20:21], v[44:45], v[34:35] op_sel_hi:[0,1,1]
	s_waitcnt lgkmcnt(12)
	v_pk_fma_f32 v[36:37], v[22:23], v[60:61], v[36:37] op_sel_hi:[0,1,1]
	v_pk_fma_f32 v[34:35], v[16:17], v[58:59], v[34:35] op_sel_hi:[0,1,1]
	s_waitcnt lgkmcnt(11)
	v_pk_fma_f32 v[36:37], v[14:15], v[76:77], v[36:37] op_sel_hi:[0,1,1]
	v_pk_fma_f32 v[34:35], v[22:23], v[62:63], v[34:35] op_sel_hi:[0,1,1]
	s_waitcnt lgkmcnt(10)
	v_pk_fma_f32 v[36:37], v[24:25], v[126:127], v[36:37] op_sel_hi:[0,1,1]
	v_pk_fma_f32 v[34:35], v[14:15], v[78:79], v[34:35] op_sel_hi:[0,1,1]
	s_waitcnt lgkmcnt(9)
	v_pk_fma_f32 v[36:37], v[12:13], v[138:139], v[36:37] op_sel_hi:[0,1,1]
	v_pk_fma_f32 v[34:35], v[24:25], v[128:129], v[34:35] op_sel_hi:[0,1,1]
	s_waitcnt lgkmcnt(8)
	v_pk_fma_f32 v[36:37], v[26:27], v[142:143], v[36:37] op_sel_hi:[0,1,1]
	v_pk_fma_f32 v[34:35], v[12:13], v[140:141], v[34:35] op_sel_hi:[0,1,1]
	s_waitcnt lgkmcnt(7)
	v_pk_fma_f32 v[36:37], v[10:11], v[146:147], v[36:37] op_sel_hi:[0,1,1]
	v_pk_fma_f32 v[34:35], v[26:27], v[144:145], v[34:35] op_sel_hi:[0,1,1]
	s_waitcnt lgkmcnt(6)
	v_pk_fma_f32 v[36:37], v[28:29], v[158:159], v[36:37] op_sel_hi:[0,1,1]
	v_pk_fma_f32 v[34:35], v[10:11], v[148:149], v[34:35] op_sel_hi:[0,1,1]
	s_waitcnt lgkmcnt(5)
	v_pk_fma_f32 v[36:37], v[8:9], v[162:163], v[36:37] op_sel_hi:[0,1,1]
	v_pk_fma_f32 v[34:35], v[28:29], v[160:161], v[34:35] op_sel_hi:[0,1,1]
	s_waitcnt lgkmcnt(4)
	v_pk_fma_f32 v[36:37], v[30:31], v[166:167], v[36:37] op_sel_hi:[0,1,1]
	v_pk_fma_f32 v[34:35], v[8:9], v[164:165], v[34:35] op_sel_hi:[0,1,1]
	s_waitcnt lgkmcnt(3)
	v_pk_fma_f32 v[36:37], v[178:179], v[6:7], v[36:37] op_sel_hi:[1,0,1]
	v_pk_fma_f32 v[34:35], v[30:31], v[168:169], v[34:35] op_sel_hi:[0,1,1]
	s_waitcnt lgkmcnt(2)
	v_pk_fma_f32 v[36:37], v[182:183], v[32:33], v[36:37] op_sel_hi:[1,0,1]
	v_pk_fma_f32 v[34:35], v[180:181], v[6:7], v[34:35] op_sel_hi:[1,0,1]
	s_waitcnt lgkmcnt(1)
	v_pk_fma_f32 v[36:37], v[198:199], v[4:5], v[36:37] op_sel_hi:[1,0,1]
	v_cndmask_b32_e64 v7, 0, v5, s[6:7]
	v_sub_f32_e32 v7, v7, v36
	v_cndmask_b32_e32 v9, 0, v5, vcc
	v_sub_f32_e32 v9, v9, v37
	v_add_f32_dpp v7, v7, v7 quad_perm:[1,0,3,2] row_mask:0xf bank_mask:0xf bound_ctrl:1
	v_pk_fma_f32 v[34:35], v[184:185], v[32:33], v[34:35] op_sel_hi:[1,0,1]
	s_nop 0
	v_add_f32_dpp v7, v7, v7 quad_perm:[2,3,0,1] row_mask:0xf bank_mask:0xf bound_ctrl:1
	v_cndmask_b32_e64 v7, v5, v7, s[6:7]
	s_waitcnt lgkmcnt(0)
	v_fma_f32 v9, -v203, v7, v9
	v_pk_fma_f32 v[34:35], v[200:201], v[4:5], v[34:35] op_sel_hi:[1,0,1]
	s_nop 0
	v_add_f32_dpp v9, v9, v9 quad_perm:[1,0,3,2] row_mask:0xf bank_mask:0xf bound_ctrl:1
	s_nop 1
	v_add_f32_dpp v9, v9, v9 quad_perm:[2,3,0,1] row_mask:0xf bank_mask:0xf bound_ctrl:1
	v_cndmask_b32_e32 v7, v7, v9, vcc
	v_cndmask_b32_e64 v9, 0, v5, s[2:3]
	v_sub_f32_e32 v9, v9, v34
	v_fma_f32 v9, -v204, v7, v9
	v_cndmask_b32_e64 v5, 0, v5, s[4:5]
	v_sub_f32_e32 v5, v5, v35
	v_add_f32_dpp v9, v9, v9 quad_perm:[1,0,3,2] row_mask:0xf bank_mask:0xf bound_ctrl:1
	s_nop 1
	v_add_f32_dpp v9, v9, v9 quad_perm:[2,3,0,1] row_mask:0xf bank_mask:0xf bound_ctrl:1
	v_cndmask_b32_e64 v7, v7, v9, s[2:3]
	v_fma_f32 v5, -v205, v7, v5
	s_nop 1
	v_add_f32_dpp v5, v5, v5 quad_perm:[1,0,3,2] row_mask:0xf bank_mask:0xf bound_ctrl:1
	s_nop 1
	v_add_f32_dpp v5, v5, v5 quad_perm:[2,3,0,1] row_mask:0xf bank_mask:0xf bound_ctrl:1
	v_cndmask_b32_e64 v5, v7, v5, s[4:5]
	s_mov_b32 s2, 0x5040100
	s_waitcnt vmcnt(12)
	v_perm_b32 v114, v206, v207, s2
	v_perm_b32 v89, v208, v209, s2
	v_perm_b32 v115, v210, v211, s2
	v_perm_b32 v116, v212, v213, s2
	v_perm_b32 v117, v214, v215, s2
	v_perm_b32 v119, v216, v217, s2
	v_perm_b32 v118, v218, v219, s2
	v_perm_b32 v120, v230, v231, s2
	v_perm_b32 v121, v232, v233, s2
	v_perm_b32 v122, v234, v235, s2
	s_and_b64 vcc, exec, s[40:41]
	s_mov_b64 s[2:3], -1
	s_cbranch_vccnz .LBB0_1089
	ds_write_b32 v3, v18 offset:55552
	ds_write_b32 v3, v20 offset:56592
	ds_write_b32 v3, v16 offset:57632
	ds_write_b32 v3, v22 offset:58672
	ds_write_b32 v3, v14 offset:59712
	ds_write_b32 v3, v24 offset:60752
	ds_write_b32 v3, v12 offset:61792
	ds_write_b32 v3, v26 offset:62832
	ds_write_b32 v3, v10 offset:63872
	ds_write_b32 v3, v28 offset:64912
	v_add_u32_e32 v3, 0xda00, v3
	s_mov_b64 s[2:3], 0
	ds_write_b32 v3, v8 offset:10144
	ds_write_b32 v3, v30 offset:11184
	ds_write_b32 v3, v6 offset:12224
	ds_write_b32 v3, v32 offset:13264
	ds_write_b32 v3, v4 offset:14304
	ds_write_b32 v3, v5 offset:15344

; __device__ __forceinline__ float sigmoidf_(float x) { return 1.0f / (1.0f + __expf(-x)); }
; __device__ __forceinline__ float softplusf_(float x) { return fmaxf(x, 0.f) + __logf(1.0f + __expf(-fabsf(x))); }
; #define AIN(i) ld_ptr(c.la + 2 * (i))
; __device__ __forceinline__ int wy_producer_task(const Ctx& c, int l, int tk, WyPre& P, unsigned* head) {
;     ...
;     if (wid == 0) { const float al = -__expf(((const float*)AIN(I_ALOG))[l * 8 + hh]), dt = ((const float*)AIN(I_DTB))[l * 8 + hh];
;         float g = al * softplusf_(P.sa + dt);
; #pragma unroll
;         for (int o = 1; o < 64; o <<= 1) { const float t = __shfl_up(g, o); if (lane >= o) g += t; }
;         GC[lane] = g; BE[lane] = sigmoidf_(P.sb); }
;     if (wid == 0 && lane == 0) *slot = gnext;
.LBB0_1093:
	ds_read_b32 v2, v1 offset:368
	s_and_b32 s1, s46, 7
	v_readlane_b32 s2, v254, 54
	s_or_b32 s30, s1, s2
	s_lshl_b64 s[2:3], s[30:31], 2
	s_waitcnt lgkmcnt(0)
	v_readfirstlane_b32 s6, v2
	ds_read_b32 v2, v1 offset:372
	s_add_u32 s6, s6, s2
	v_add_u32_e32 v6, -1, v223
	s_waitcnt lgkmcnt(0)
	v_readfirstlane_b32 s7, v2
	s_addc_u32 s7, s7, s3
	s_nop 3
	global_load_dword v2, v1, s[6:7]
	ds_read_b32 v3, v1 offset:376
	s_waitcnt lgkmcnt(0)
	v_readfirstlane_b32 s1, v3
	ds_read_b32 v3, v1 offset:380
	s_add_u32 s2, s1, s2
	s_mov_b32 s1, 0xbfb8aa3b
	s_waitcnt lgkmcnt(0)
	v_readfirstlane_b32 s6, v3
	s_addc_u32 s3, s6, s3
	global_load_dword v3, v1, s[2:3]
	s_waitcnt vmcnt(1)
	v_mul_f32_e32 v2, 0x3fb8aa3b, v2
	v_exp_f32_e32 v2, v2
	s_waitcnt vmcnt(0)
	v_add_f32_e32 v3, v111, v3
	v_max_f32_e32 v4, 0, v3
	v_mul_f32_e64 v3, |v3|, s1
	v_exp_f32_e32 v3, v3
	s_mov_b32 s1, 0x800000
	v_add_f32_e32 v3, 1.0, v3
	v_cmp_gt_f32_e32 vcc, s1, v3
	s_mov_b32 s1, 0x3f317217
	s_nop 0
	v_cndmask_b32_e64 v5, 0, 32, vcc
	v_ldexp_f32 v3, v3, v5
	v_log_f32_e32 v3, v3
	s_nop 0
	v_mul_f32_e32 v5, 0x3f317217, v3
	v_fma_f32 v5, v3, s1, -v5
	v_fmac_f32_e32 v5, 0x3377d1cf, v3
	s_mov_b32 s1, 0x7f800000
	v_fmac_f32_e32 v5, 0x3f317217, v3
	v_cmp_lt_f32_e64 s[2:3], |v3|, s1
	s_nop 1
	v_cndmask_b32_e64 v3, v3, v5, s[2:3]
	v_mov_b32_e32 v5, 0x41b17218
	v_cndmask_b32_e32 v5, 0, v5, vcc
	v_sub_f32_e32 v3, v3, v5
	v_and_b32_e32 v5, 64, v223
	v_cmp_lt_i32_e32 vcc, v6, v5
	v_add_f32_e32 v3, v4, v3
	v_mul_f32_e64 v4, v3, -v2
	v_cndmask_b32_e32 v6, v6, v223, vcc
	v_lshlrev_b32_e32 v6, 2, v6
	ds_bpermute_b32 v6, v6, v4
	v_cmp_gt_i32_e32 vcc, 1, v88
	s_waitcnt lgkmcnt(0)
	v_fma_f32 v2, v3, -v2, v6
	v_add_u32_e32 v3, -2, v223
	v_cndmask_b32_e32 v2, v2, v4, vcc
	v_cmp_lt_i32_e32 vcc, v3, v5
	s_nop 1
	v_cndmask_b32_e32 v3, v3, v223, vcc
	v_lshlrev_b32_e32 v3, 2, v3
	ds_bpermute_b32 v3, v3, v2
	v_cmp_gt_i32_e32 vcc, 2, v88
	s_waitcnt lgkmcnt(0)
	v_add_f32_e32 v3, v2, v3
	v_cndmask_b32_e32 v2, v3, v2, vcc
	v_add_u32_e32 v3, -4, v223
	v_cmp_lt_i32_e32 vcc, v3, v5
	s_nop 1
	v_cndmask_b32_e32 v3, v3, v223, vcc
	v_lshlrev_b32_e32 v3, 2, v3
	ds_bpermute_b32 v3, v3, v2
	v_cmp_gt_i32_e32 vcc, 4, v88
	s_waitcnt lgkmcnt(0)
	v_add_f32_e32 v3, v2, v3
	v_cndmask_b32_e32 v2, v3, v2, vcc
	v_add_u32_e32 v3, -8, v223
	v_cmp_lt_i32_e32 vcc, v3, v5
	s_nop 1
	v_cndmask_b32_e32 v3, v3, v223, vcc
	v_lshlrev_b32_e32 v3, 2, v3
	ds_bpermute_b32 v3, v3, v2
	v_cmp_gt_i32_e32 vcc, 8, v88
	s_waitcnt lgkmcnt(0)
	v_add_f32_e32 v3, v2, v3
	v_cndmask_b32_e32 v2, v3, v2, vcc
	v_add_u32_e32 v3, -16, v223
	v_cmp_lt_i32_e32 vcc, v3, v5
	s_nop 1
	v_cndmask_b32_e32 v3, v3, v223, vcc
	v_lshlrev_b32_e32 v3, 2, v3
	ds_bpermute_b32 v3, v3, v2
	v_cmp_gt_i32_e32 vcc, 16, v88
	s_waitcnt lgkmcnt(0)
	v_add_f32_e32 v3, v2, v3
	v_cndmask_b32_e32 v2, v3, v2, vcc
	v_subrev_u32_e32 v3, 32, v223
	v_cmp_lt_i32_e32 vcc, v3, v5
	s_nop 1
	v_cndmask_b32_e32 v3, v3, v223, vcc
	v_lshlrev_b32_e32 v3, 2, v3
	ds_bpermute_b32 v3, v3, v2
	v_cmp_gt_i32_e32 vcc, 32, v88
	s_waitcnt lgkmcnt(0)
	v_add_f32_e32 v3, v2, v3
	v_cndmask_b32_e32 v2, v3, v2, vcc
	v_lshl_add_u32 v3, v88, 2, 0
	v_add_u32_e32 v4, 0x11b00, v3
	ds_write_b32 v4, v2
	v_mul_f32_e32 v2, 0xbfb8aa3b, v109
	v_exp_f32_e32 v2, v2
	v_add_u32_e32 v3, 0x11c00, v3
	v_add_f32_e32 v2, 1.0, v2
	v_div_scale_f32 v4, s[2:3], v2, v2, 1.0
	v_rcp_f32_e32 v5, v4
	s_nop 0
	v_fma_f32 v6, -v4, v5, 1.0
	v_fmac_f32_e32 v5, v6, v5
	v_div_scale_f32 v6, vcc, 1.0, v2, 1.0
	v_mul_f32_e32 v7, v6, v5
	v_fma_f32 v8, -v4, v7, v6
	v_fmac_f32_e32 v7, v8, v5
	v_fma_f32 v4, -v4, v7, v6
	v_div_fmas_f32 v4, v4, v5, v7
	v_div_fixup_f32 v2, v4, v2, 1.0
	ds_write_b32 v3, v2
	s_and_saveexec_b64 s[2:3], s[4:5]
	s_cbranch_execnz .LBB0_966
	s_branch .LBB0_967
.LBB0_1099:
	s_ashr_i32 s19, s94, 31
	s_add_u32 s20, s10, s94
	s_addc_u32 s19, s11, s19
	s_mulk_i32 s19, 0x1c00
	s_mul_hi_u32 s22, s20, 0x1c00
	s_add_i32 s22, s22, s19
	s_mulk_i32 s20, 0x1c00
	s_add_u32 s19, s8, s20
	s_addc_u32 s20, s9, s22
	s_lshl_b32 s22, s12, 1
	s_add_u32 s22, s19, s22
	s_addc_u32 s23, s20, 0
	v_lshl_add_u64 v[2:3], v[82:83], 1, s[22:23]
	v_add_co_u32_e32 v2, vcc, 0xfd00000, v2
	s_nop 1
	v_addc_co_u32_e32 v3, vcc, 0, v3, vcc
	global_load_ushort v8, v[2:3], off offset:2560 nt
	s_and_b64 vcc, exec, s[2:3]
	s_cbranch_vccnz .LBB0_924
